# cross-unit prefetch in phase 7 (moe gate/up): next unit's gather indices loaded mid-loop, its first two LDS-DMA stages issued before the epilogue
# speedup vs baseline: 1.0750x; 1.0028x over previous
.LBB0_836:
	s_cmpk_gt_i32 s47, 0x7ff
	s_cbranch_scc1 .LBB0_840
	v_writelane_b32 v196, s0, 26
	v_readlane_b32 s72, v197, 34
	s_lshl_b32 s38, s47, 7
	v_writelane_b32 v196, s1, 27
	s_lshl_b32 s39, s46, 7
	v_readlane_b32 s8, v196, 6
	v_readlane_b32 s10, v196, 8
	v_readlane_b32 s11, v196, 9
	v_readlane_b32 s12, v196, 10
	v_readlane_b32 s13, v196, 11
	v_readlane_b32 s14, v196, 12
	v_readlane_b32 s15, v196, 13
	v_readlane_b32 s16, v196, 14
	v_readlane_b32 s17, v196, 15
	v_readlane_b32 s18, v196, 16
	v_readlane_b32 s19, v196, 17
	v_readlane_b32 s20, v196, 18
	v_readlane_b32 s21, v196, 19
	s_mov_b32 s3, 0
	v_mov_b32_e32 v67, 0
	s_mov_b64 s[96:97], 0x100
	s_add_i32 s56, 0, 0xc000
	s_mov_b64 s[0:1], 0x180
	s_add_i32 s57, 0, 0x18000
	s_mov_b64 s[6:7], 0x200
	s_mov_b64 s[24:25], 0x500
	s_mov_b32 s58, s47
	s_mov_b64 s[26:27], 0x580
	s_mov_b64 s[28:29], 0x600
	s_mov_b64 s[30:31], 0x680
	s_mov_b64 s[34:35], 0x700
	s_mov_b64 s[36:37], 0x780
	v_readlane_b32 s9, v196, 7
	v_readlane_b32 s22, v196, 20
	v_readlane_b32 s23, v196, 21
	s_mov_b64 s[18:19], 0x400
	s_mov_b64 s[16:17], 0x380
	s_mov_b64 s[14:15], 0x300
	s_mov_b64 s[12:13], 0x280
	s_mov_b64 s[10:11], 0x80
	s_mov_b64 s[20:21], 0x480
	v_readlane_b32 s82, v197, 44
	v_readlane_b32 s83, v197, 45
	v_readlane_b32 s73, v197, 35
	v_readlane_b32 s74, v197, 36
	v_readlane_b32 s75, v197, 37
	v_readlane_b32 s76, v197, 38
	v_readlane_b32 s77, v197, 39
	v_readlane_b32 s78, v197, 40
	v_readlane_b32 s79, v197, 41
	v_readlane_b32 s80, v197, 42
	v_readlane_b32 s81, v197, 43
	v_readlane_b32 s84, v197, 46
	v_readlane_b32 s85, v197, 47
	v_readlane_b32 s86, v197, 48
	v_readlane_b32 s87, v197, 49
	s_mov_b32 s98, s58
	s_mov_b32 s99, 0

.Lremap_done_7:
	s_lshl_b32 s38, s58, 7
	s_bfe_u32 s2, s58, 0x20002
	s_ashr_i32 s60, s58, 7
	s_lshl_b32 s4, s2, 4
	s_add_i32 s46, s4, s60
	v_mov_b32_e32 v1, v0
	s_lshl_b32 s5, s46, 9
	s_and_b32 s4, s38, 0x180
	s_waitcnt vmcnt(0) lgkmcnt(0)
	s_barrier
	s_or_b32 s5, s5, s4
	v_ashrrev_i32_e32 v2, 3, v1
	v_add_u32_e32 v4, s5, v2
	v_ashrrev_i32_e32 v5, 31, v4
	v_lshl_add_u64 v[4:5], v[4:5], 2, s[52:53]
	s_cmp_eq_u32 s99, 1
	s_cbranch_scc1 .Lpf7_have_idx
	global_load_dword v6, v[4:5], off
	global_load_dword v8, v[4:5], off offset:256
	s_branch .Lpf7_idx_join
.Lpf7_have_idx:
	v_mov_b32_e32 v6, v200
	v_mov_b32_e32 v8, v201
.Lpf7_idx_join:
	s_ashr_i32 s61, s60, 31
	v_lshrrev_b32_e32 v3, 4, v1
	s_bfe_u32 s59, s58, 0x30004
	s_lshl_b64 s[60:61], s[60:61], 22
	v_xor_b32_e32 v3, v3, v1
	s_add_u32 s5, s82, s60
	s_addc_u32 s33, s83, s61
	s_lshl_b32 s47, s59, 19
	v_lshlrev_b32_e32 v3, 4, v3
	s_add_u32 s60, s5, s47
	v_and_b32_e32 v66, 0x70, v3
	v_ashrrev_i32_e32 v3, 31, v2
	s_addc_u32 s61, s33, 0
	v_lshlrev_b64 v[2:3], 11, v[2:3]
	s_lshl_b32 s2, s2, 12
	v_lshl_add_u64 v[2:3], s[60:61], 0, v[2:3]
	v_mov_b32_e32 v14, v0
	v_lshl_add_u64 v[2:3], v[2:3], 0, v[66:67]
	s_mov_b64 s[60:61], 0x20000
	s_mov_b64 s[66:67], 0x20080
	s_mov_b64 s[68:69], 0x60080
	v_lshrrev_b32_e32 v15, 4, v14
	v_bfe_u32 v16, v14, 4, 2
	v_and_b32_e32 v17, 15, v14
	s_mov_b64 s[72:73], 0x20100
	s_mov_b64 s[74:75], 0x60100
	s_waitcnt vmcnt(1)
	v_ashrrev_i32_e32 v7, 31, v6
	s_waitcnt vmcnt(0)
	v_ashrrev_i32_e32 v9, 31, v8
	v_lshl_add_u64 v[4:5], v[6:7], 0, s[2:3]
	v_lshl_add_u64 v[6:7], v[8:9], 0, s[2:3]
	v_readfirstlane_b32 s2, v14
	v_lshl_add_u64 v[8:9], v[2:3], 0, s[60:61]
	s_mov_b64 s[60:61], 0x40000
	s_lshl_b32 s2, s2, 4
	v_lshlrev_b64 v[4:5], 11, v[4:5]
	v_lshl_add_u64 v[10:11], v[2:3], 0, s[60:61]
	s_mov_b64 s[60:61], 0x60000
	s_and_b32 s2, s2, 0xfffffc00
	v_lshl_add_u64 v[4:5], s[8:9], 0, v[4:5]
	v_lshlrev_b64 v[6:7], 11, v[6:7]
	v_lshl_add_u64 v[12:13], v[2:3], 0, s[60:61]
	s_add_i32 s61, s2, 0
	v_lshl_add_u64 v[4:5], v[4:5], 0, v[66:67]
	v_lshl_add_u64 v[6:7], s[8:9], 0, v[6:7]
	s_mov_b32 m0, s61
	s_add_i32 s47, s61, 0x2000
	v_lshl_add_u64 v[6:7], v[6:7], 0, v[66:67]
	s_cmp_eq_u32 s99, 1
	s_cbranch_scc1 .Lpf7_skip_glds
	global_load_lds_dwordx4 v[4:5], off
	s_mov_b32 m0, s47
	s_add_i32 s60, s61, 0x4000
	global_load_lds_dwordx4 v[6:7], off
	s_mov_b32 m0, s60
	s_add_i32 s33, s61, 0x6000
	global_load_lds_dwordx4 v[2:3], off
	s_mov_b32 m0, s33
	s_add_i32 s5, s61, 0x8000
	global_load_lds_dwordx4 v[8:9], off
	s_mov_b32 m0, s5
	s_add_i32 s2, s61, 0xa000
	global_load_lds_dwordx4 v[10:11], off
	s_mov_b32 m0, s2
	s_add_i32 s63, s61, 0xc000
	global_load_lds_dwordx4 v[12:13], off
	v_lshl_add_u64 v[8:9], v[4:5], 0, s[10:11]
	s_mov_b32 m0, s63
	s_add_i32 s62, s61, 0xe000
	global_load_lds_dwordx4 v[8:9], off
	v_lshl_add_u64 v[8:9], v[6:7], 0, s[10:11]
	s_mov_b32 m0, s62
	s_add_i32 s64, s61, 0x10000
	global_load_lds_dwordx4 v[8:9], off
	v_lshl_add_u64 v[8:9], v[2:3], 0, s[10:11]
	s_mov_b32 m0, s64
	s_add_i32 s65, s61, 0x12000
	global_load_lds_dwordx4 v[8:9], off
	v_lshl_add_u64 v[8:9], v[2:3], 0, s[66:67]
	s_mov_b32 m0, s65
	s_mov_b64 s[66:67], 0x40080
	global_load_lds_dwordx4 v[8:9], off
	v_lshl_add_u64 v[8:9], v[2:3], 0, s[66:67]
	s_add_i32 s66, s61, 0x14000
	s_mov_b32 m0, s66
	s_add_i32 s67, s61, 0x16000
	global_load_lds_dwordx4 v[8:9], off
	v_lshl_add_u64 v[8:9], v[2:3], 0, s[68:69]
	s_mov_b32 m0, s67
	s_mov_b32 s68, 0x1ffffc0
	global_load_lds_dwordx4 v[8:9], off
	s_branch .Lpf7_glds_join
.Lpf7_skip_glds:
	s_add_i32 s60, s61, 0x4000
	s_add_i32 s33, s61, 0x6000
	s_add_i32 s5, s61, 0x8000
	s_add_i32 s2, s61, 0xa000
	s_add_i32 s63, s61, 0xc000
	s_add_i32 s62, s61, 0xe000
	s_add_i32 s64, s61, 0x10000
	s_add_i32 s65, s61, 0x12000
	s_mov_b64 s[66:67], 0x40080
	s_add_i32 s66, s61, 0x14000
	s_add_i32 s67, s61, 0x16000
	s_mov_b32 s68, 0x1ffffc0
.Lpf7_glds_join:
	v_bfe_u32 v8, v14, 1, 3
	v_lshrrev_b32_e32 v9, 2, v14
	v_and_or_b32 v9, v9, s68, v17
	v_lshlrev_b32_e32 v10, 7, v14
	v_bitop3_b32 v11, v15, v8, 3 bitop3:0x6c
	v_bitop3_b32 v8, v16, v8, 4 bitop3:0x36
	v_lshlrev_b32_e32 v9, 7, v9
	v_and_b32_e32 v60, 0x6780, v10
	v_lshlrev_b32_e32 v11, 4, v11
	v_lshlrev_b32_e32 v61, 4, v8
	v_add_u32_e32 v10, 0x4000, v60
	v_or_b32_e32 v64, v11, v9
	v_or_b32_e32 v66, v61, v9
	v_or_b32_e32 v9, v11, v60
	s_add_i32 s68, s61, 0x18000
	s_waitcnt vmcnt(6)
	s_barrier
	v_or_b32_e32 v65, v11, v10
	v_or_b32_e32 v152, v61, v10
	v_add_u32_e32 v8, 0, v64
	v_add_u32_e32 v9, 0, v9
	v_lshl_add_u64 v[10:11], v[4:5], 0, s[96:97]
	s_mov_b32 m0, s68
	s_add_i32 s69, s61, 0x1a000
	ds_read_b128 v[12:15], v8
	ds_read_b128 v[16:19], v8 offset:2048
	ds_read_b128 v[20:23], v8 offset:4096
	ds_read_b128 v[24:27], v8 offset:6144
	ds_read_b128 v[28:31], v9 offset:22528
	ds_read_b128 v[32:35], v9 offset:20480
	ds_read_b128 v[36:39], v9 offset:18432
	ds_read_b128 v[40:43], v9 offset:16384
	global_load_lds_dwordx4 v[10:11], off
	v_lshl_add_u64 v[10:11], v[6:7], 0, s[96:97]
	s_mov_b32 m0, s69
	s_add_i32 s70, s61, 0x1c000
	global_load_lds_dwordx4 v[10:11], off
	v_lshl_add_u64 v[10:11], v[2:3], 0, s[96:97]
	s_mov_b32 m0, s70
	s_add_i32 s71, s61, 0x1e000
	global_load_lds_dwordx4 v[10:11], off
	v_lshl_add_u64 v[10:11], v[2:3], 0, s[72:73]
	s_mov_b32 m0, s71
	s_mov_b64 s[72:73], 0x40100
	global_load_lds_dwordx4 v[10:11], off
	v_lshl_add_u64 v[10:11], v[2:3], 0, s[72:73]
	s_add_i32 s72, s61, 0x20000
	s_mov_b32 m0, s72
	s_add_i32 s73, s61, 0x22000
	global_load_lds_dwordx4 v[10:11], off
	v_lshl_add_u64 v[10:11], v[2:3], 0, s[74:75]
	s_mov_b32 m0, s73
	s_nop 0
	global_load_lds_dwordx4 v[10:11], off
	v_or_b32_e32 v11, v61, v60
	v_add_u32_e32 v10, 0, v66
	v_add_u32_e32 v11, 0, v11
	ds_read_b128 v[44:47], v10
	ds_read_b128 v[48:51], v10 offset:2048
	ds_read_b128 v[52:55], v10 offset:4096
	ds_read_b128 v[56:59], v10 offset:6144
	ds_read_b128 v[60:63], v11 offset:16384
	ds_read_b128 v[68:71], v11 offset:18432
	ds_read_b128 v[72:75], v11 offset:20480
	ds_read_b128 v[76:79], v11 offset:22528
	s_waitcnt lgkmcnt(8)
	v_mfma_f32_16x16x32_bf16 v[80:83], v[40:43], v[12:15], 0
	v_mfma_f32_16x16x32_bf16 v[84:87], v[36:39], v[12:15], 0
	v_mfma_f32_16x16x32_bf16 v[88:91], v[32:35], v[12:15], 0
	v_mfma_f32_16x16x32_bf16 v[92:95], v[28:31], v[12:15], 0
	v_mfma_f32_16x16x32_bf16 v[96:99], v[40:43], v[16:19], 0
	v_mfma_f32_16x16x32_bf16 v[100:103], v[36:39], v[16:19], 0
	v_mfma_f32_16x16x32_bf16 v[104:107], v[32:35], v[16:19], 0
	v_mfma_f32_16x16x32_bf16 v[14:17], v[28:31], v[16:19], 0
	v_mfma_f32_16x16x32_bf16 v[108:111], v[40:43], v[20:23], 0
	v_mfma_f32_16x16x32_bf16 v[112:115], v[36:39], v[20:23], 0
	v_mfma_f32_16x16x32_bf16 v[116:119], v[32:35], v[20:23], 0
	v_mfma_f32_16x16x32_bf16 v[18:21], v[28:31], v[20:23], 0
	v_mfma_f32_16x16x32_bf16 v[40:43], v[40:43], v[24:27], 0
	v_mfma_f32_16x16x32_bf16 v[36:39], v[36:39], v[24:27], 0
	v_mfma_f32_16x16x32_bf16 v[32:35], v[32:35], v[24:27], 0
	v_mfma_f32_16x16x32_bf16 v[22:25], v[28:31], v[24:27], 0
	s_waitcnt vmcnt(6) lgkmcnt(0)
	s_barrier
	v_add_u32_e32 v12, s56, v65
	ds_read_b128 v[26:29], v8 offset:49152
	ds_read_b128 v[120:123], v8 offset:51200
	ds_read_b128 v[124:127], v8 offset:53248
	ds_read_b128 v[128:131], v8 offset:55296
	ds_read_b128 v[132:135], v12
	ds_read_b128 v[136:139], v12 offset:2048
	ds_read_b128 v[140:143], v12 offset:4096
	ds_read_b128 v[144:147], v12 offset:6144
	v_mfma_f32_16x16x32_bf16 v[80:83], v[60:63], v[44:47], v[80:83]
	v_mfma_f32_16x16x32_bf16 v[84:87], v[68:71], v[44:47], v[84:87]
	v_mfma_f32_16x16x32_bf16 v[88:91], v[72:75], v[44:47], v[88:91]
	v_mfma_f32_16x16x32_bf16 v[44:47], v[76:79], v[44:47], v[92:95]
	v_mfma_f32_16x16x32_bf16 v[92:95], v[60:63], v[48:51], v[96:99]
	v_mfma_f32_16x16x32_bf16 v[96:99], v[68:71], v[48:51], v[100:103]
	v_mfma_f32_16x16x32_bf16 v[100:103], v[72:75], v[48:51], v[104:107]
	v_mfma_f32_16x16x32_bf16 v[14:17], v[76:79], v[48:51], v[14:17]
	v_mfma_f32_16x16x32_bf16 v[48:51], v[60:63], v[52:55], v[108:111]
	v_mfma_f32_16x16x32_bf16 v[104:107], v[68:71], v[52:55], v[112:115]
	v_mfma_f32_16x16x32_bf16 v[108:111], v[72:75], v[52:55], v[116:119]
	v_mfma_f32_16x16x32_bf16 v[18:21], v[76:79], v[52:55], v[18:21]
	v_mfma_f32_16x16x32_bf16 v[40:43], v[60:63], v[56:59], v[40:43]
	v_mfma_f32_16x16x32_bf16 v[36:39], v[68:71], v[56:59], v[36:39]
	v_mfma_f32_16x16x32_bf16 v[30:33], v[72:75], v[56:59], v[32:35]
	v_mfma_f32_16x16x32_bf16 v[22:25], v[76:79], v[56:59], v[22:25]
	s_mov_b32 m0, s61
	s_nop 0
	v_lshl_add_u64 v[34:35], v[4:5], 0, s[0:1]
	global_load_lds_dwordx4 v[34:35], off
	v_lshl_add_u64 v[34:35], v[6:7], 0, s[0:1]
	s_mov_b32 m0, s47
	s_mov_b64 s[74:75], 0x20180
	global_load_lds_dwordx4 v[34:35], off
	v_lshl_add_u64 v[34:35], v[2:3], 0, s[0:1]
	s_mov_b32 m0, s60
	v_add_u32_e32 v13, s56, v152
	global_load_lds_dwordx4 v[34:35], off
	v_lshl_add_u64 v[34:35], v[2:3], 0, s[74:75]
	s_mov_b32 m0, s33
	s_mov_b64 s[74:75], 0x40180
	global_load_lds_dwordx4 v[34:35], off
	v_lshl_add_u64 v[34:35], v[2:3], 0, s[74:75]
	s_mov_b32 m0, s5
	s_mov_b64 s[74:75], 0x60180
	global_load_lds_dwordx4 v[34:35], off
	v_lshl_add_u64 v[34:35], v[2:3], 0, s[74:75]
	s_mov_b32 m0, s2
	s_nop 0
	global_load_lds_dwordx4 v[34:35], off
	ds_read_b128 v[52:55], v10 offset:49152
	ds_read_b128 v[56:59], v10 offset:51200
	ds_read_b128 v[60:63], v10 offset:53248
	ds_read_b128 v[68:71], v10 offset:55296
	ds_read_b128 v[72:75], v13
	ds_read_b128 v[76:79], v13 offset:2048
	ds_read_b128 v[112:115], v13 offset:4096
	ds_read_b128 v[116:119], v13 offset:6144
	s_waitcnt lgkmcnt(8)
	v_mfma_f32_16x16x32_bf16 v[80:83], v[132:135], v[26:29], v[80:83]
	v_mfma_f32_16x16x32_bf16 v[84:87], v[136:139], v[26:29], v[84:87]
	v_mfma_f32_16x16x32_bf16 v[88:91], v[140:143], v[26:29], v[88:91]
	v_mfma_f32_16x16x32_bf16 v[26:29], v[144:147], v[26:29], v[44:47]
	v_mfma_f32_16x16x32_bf16 v[44:47], v[132:135], v[120:123], v[92:95]
	v_mfma_f32_16x16x32_bf16 v[92:95], v[136:139], v[120:123], v[96:99]
	v_mfma_f32_16x16x32_bf16 v[96:99], v[140:143], v[120:123], v[100:103]
	v_mfma_f32_16x16x32_bf16 v[100:103], v[144:147], v[120:123], v[14:17]
	v_mfma_f32_16x16x32_bf16 v[48:51], v[132:135], v[124:127], v[48:51]
	v_mfma_f32_16x16x32_bf16 v[104:107], v[136:139], v[124:127], v[104:107]
	v_mfma_f32_16x16x32_bf16 v[108:111], v[140:143], v[124:127], v[108:111]
	v_mfma_f32_16x16x32_bf16 v[16:19], v[144:147], v[124:127], v[18:21]
	v_mfma_f32_16x16x32_bf16 v[40:43], v[132:135], v[128:131], v[40:43]
	v_mfma_f32_16x16x32_bf16 v[34:37], v[136:139], v[128:131], v[36:39]
	v_mfma_f32_16x16x32_bf16 v[30:33], v[140:143], v[128:131], v[30:33]
	v_mfma_f32_16x16x32_bf16 v[20:23], v[144:147], v[128:131], v[22:25]
	s_waitcnt vmcnt(6) lgkmcnt(0)
	s_barrier
	v_add_u32_e32 v14, s57, v64
	v_add_u32_e32 v15, s57, v65
	ds_read_b128 v[120:123], v14
	ds_read_b128 v[124:127], v14 offset:2048
	ds_read_b128 v[128:131], v14 offset:4096
	ds_read_b128 v[132:135], v14 offset:6144
	ds_read_b128 v[136:139], v15
	ds_read_b128 v[140:143], v15 offset:2048
	ds_read_b128 v[144:147], v15 offset:4096
	ds_read_b128 v[148:151], v15 offset:6144
	v_mfma_f32_16x16x32_bf16 v[80:83], v[72:75], v[52:55], v[80:83]
	v_mfma_f32_16x16x32_bf16 v[84:87], v[76:79], v[52:55], v[84:87]
	v_mfma_f32_16x16x32_bf16 v[88:91], v[112:115], v[52:55], v[88:91]
	v_mfma_f32_16x16x32_bf16 v[24:27], v[116:119], v[52:55], v[26:29]
	v_mfma_f32_16x16x32_bf16 v[44:47], v[72:75], v[56:59], v[44:47]
	v_mfma_f32_16x16x32_bf16 v[52:55], v[76:79], v[56:59], v[92:95]
	v_mfma_f32_16x16x32_bf16 v[92:95], v[112:115], v[56:59], v[96:99]
	v_mfma_f32_16x16x32_bf16 v[56:59], v[116:119], v[56:59], v[100:103]
	v_mfma_f32_16x16x32_bf16 v[48:51], v[72:75], v[60:63], v[48:51]
	v_mfma_f32_16x16x32_bf16 v[96:99], v[76:79], v[60:63], v[104:107]
	v_mfma_f32_16x16x32_bf16 v[100:103], v[112:115], v[60:63], v[108:111]
	v_mfma_f32_16x16x32_bf16 v[60:63], v[116:119], v[60:63], v[16:19]
	v_mfma_f32_16x16x32_bf16 v[38:41], v[72:75], v[68:71], v[40:43]
	v_mfma_f32_16x16x32_bf16 v[34:37], v[76:79], v[68:71], v[34:37]
	v_mfma_f32_16x16x32_bf16 v[28:31], v[112:115], v[68:71], v[30:33]
	v_mfma_f32_16x16x32_bf16 v[18:21], v[116:119], v[68:71], v[20:23]
	s_mov_b32 m0, s63
	v_lshl_add_u64 v[16:17], v[4:5], 0, s[6:7]
	global_load_lds_dwordx4 v[16:17], off
	v_lshl_add_u64 v[16:17], v[6:7], 0, s[6:7]
	s_mov_b32 m0, s62
	s_mov_b64 s[74:75], 0x20200
	global_load_lds_dwordx4 v[16:17], off
	v_lshl_add_u64 v[16:17], v[2:3], 0, s[6:7]
	s_mov_b32 m0, s64
	s_nop 0
	global_load_lds_dwordx4 v[16:17], off
	v_lshl_add_u64 v[16:17], v[2:3], 0, s[74:75]
	s_mov_b32 m0, s65
	s_mov_b64 s[74:75], 0x40200
	global_load_lds_dwordx4 v[16:17], off
	v_lshl_add_u64 v[16:17], v[2:3], 0, s[74:75]
	s_mov_b32 m0, s66
	s_mov_b64 s[74:75], 0x60200
	global_load_lds_dwordx4 v[16:17], off
	v_lshl_add_u64 v[16:17], v[2:3], 0, s[74:75]
	s_mov_b32 m0, s67
	s_nop 0
	global_load_lds_dwordx4 v[16:17], off
	v_add_u32_e32 v16, s57, v66
	v_add_u32_e32 v17, s57, v152
	ds_read_b128 v[68:71], v16
	ds_read_b128 v[72:75], v16 offset:2048
	ds_read_b128 v[76:79], v16 offset:4096
	ds_read_b128 v[104:107], v16 offset:6144
	ds_read_b128 v[108:111], v17
	ds_read_b128 v[112:115], v17 offset:2048
	ds_read_b128 v[116:119], v17 offset:4096
	ds_read_b128 v[152:155], v17 offset:6144
	s_waitcnt lgkmcnt(8)
	v_mfma_f32_16x16x32_bf16 v[80:83], v[136:139], v[120:123], v[80:83]
	v_mfma_f32_16x16x32_bf16 v[84:87], v[140:143], v[120:123], v[84:87]
	v_mfma_f32_16x16x32_bf16 v[88:91], v[144:147], v[120:123], v[88:91]
	v_mfma_f32_16x16x32_bf16 v[22:25], v[148:151], v[120:123], v[24:27]
	v_mfma_f32_16x16x32_bf16 v[42:45], v[136:139], v[124:127], v[44:47]
	v_mfma_f32_16x16x32_bf16 v[52:55], v[140:143], v[124:127], v[52:55]
	v_mfma_f32_16x16x32_bf16 v[92:95], v[144:147], v[124:127], v[92:95]
	v_mfma_f32_16x16x32_bf16 v[56:59], v[148:151], v[124:127], v[56:59]
	v_mfma_f32_16x16x32_bf16 v[46:49], v[136:139], v[128:131], v[48:51]
	v_mfma_f32_16x16x32_bf16 v[96:99], v[140:143], v[128:131], v[96:99]
	v_mfma_f32_16x16x32_bf16 v[100:103], v[144:147], v[128:131], v[100:103]
	v_mfma_f32_16x16x32_bf16 v[60:63], v[148:151], v[128:131], v[60:63]
	v_mfma_f32_16x16x32_bf16 v[38:41], v[136:139], v[132:135], v[38:41]
	v_mfma_f32_16x16x32_bf16 v[32:35], v[140:143], v[132:135], v[34:37]
	v_mfma_f32_16x16x32_bf16 v[26:29], v[144:147], v[132:135], v[28:31]
	v_mfma_f32_16x16x32_bf16 v[18:21], v[148:151], v[132:135], v[18:21]
	s_waitcnt vmcnt(6) lgkmcnt(0)
	s_barrier
	ds_read_b128 v[120:123], v8
	ds_read_b128 v[124:127], v8 offset:2048
	ds_read_b128 v[128:131], v8 offset:4096
	ds_read_b128 v[132:135], v8 offset:6144
	ds_read_b128 v[136:139], v9 offset:16384
	ds_read_b128 v[140:143], v9 offset:18432
	ds_read_b128 v[144:147], v9 offset:20480
	ds_read_b128 v[148:151], v9 offset:22528
	v_mfma_f32_16x16x32_bf16 v[80:83], v[108:111], v[68:71], v[80:83]
	v_mfma_f32_16x16x32_bf16 v[84:87], v[112:115], v[68:71], v[84:87]
	v_mfma_f32_16x16x32_bf16 v[88:91], v[116:119], v[68:71], v[88:91]
	v_mfma_f32_16x16x32_bf16 v[22:25], v[152:155], v[68:71], v[22:25]
	v_mfma_f32_16x16x32_bf16 v[42:45], v[108:111], v[72:75], v[42:45]
	v_mfma_f32_16x16x32_bf16 v[50:53], v[112:115], v[72:75], v[52:55]
	v_mfma_f32_16x16x32_bf16 v[68:71], v[116:119], v[72:75], v[92:95]
	v_mfma_f32_16x16x32_bf16 v[54:57], v[152:155], v[72:75], v[56:59]
	v_mfma_f32_16x16x32_bf16 v[46:49], v[108:111], v[76:79], v[46:49]
	v_mfma_f32_16x16x32_bf16 v[72:75], v[112:115], v[76:79], v[96:99]
	v_mfma_f32_16x16x32_bf16 v[92:95], v[116:119], v[76:79], v[100:103]
	v_mfma_f32_16x16x32_bf16 v[58:61], v[152:155], v[76:79], v[60:63]
	v_mfma_f32_16x16x32_bf16 v[36:39], v[108:111], v[104:107], v[38:41]
	v_mfma_f32_16x16x32_bf16 v[30:33], v[112:115], v[104:107], v[32:35]
	v_mfma_f32_16x16x32_bf16 v[26:29], v[116:119], v[104:107], v[26:29]
	v_mfma_f32_16x16x32_bf16 v[18:21], v[152:155], v[104:107], v[18:21]
	s_mov_b32 m0, s68
	v_lshl_add_u64 v[34:35], v[4:5], 0, s[12:13]
	global_load_lds_dwordx4 v[34:35], off
	v_lshl_add_u64 v[34:35], v[6:7], 0, s[12:13]
	s_mov_b32 m0, s69
	s_mov_b64 s[74:75], 0x20280
	global_load_lds_dwordx4 v[34:35], off
	v_lshl_add_u64 v[34:35], v[2:3], 0, s[12:13]
	s_mov_b32 m0, s70
	s_nop 0
	global_load_lds_dwordx4 v[34:35], off
	v_lshl_add_u64 v[34:35], v[2:3], 0, s[74:75]
	s_mov_b32 m0, s71
	s_mov_b64 s[74:75], 0x40280
	global_load_lds_dwordx4 v[34:35], off
	v_lshl_add_u64 v[34:35], v[2:3], 0, s[74:75]
	s_mov_b32 m0, s72
	s_mov_b64 s[74:75], 0x60280
	global_load_lds_dwordx4 v[34:35], off
	v_lshl_add_u64 v[34:35], v[2:3], 0, s[74:75]
	s_mov_b32 m0, s73
	s_nop 0
	global_load_lds_dwordx4 v[34:35], off
	ds_read_b128 v[62:65], v10
	ds_read_b128 v[76:79], v10 offset:2048
	ds_read_b128 v[96:99], v10 offset:4096
	ds_read_b128 v[100:103], v10 offset:6144
	ds_read_b128 v[104:107], v11 offset:16384
	ds_read_b128 v[108:111], v11 offset:18432
	ds_read_b128 v[112:115], v11 offset:20480
	ds_read_b128 v[116:119], v11 offset:22528
	s_waitcnt lgkmcnt(8)
	v_mfma_f32_16x16x32_bf16 v[80:83], v[136:139], v[120:123], v[80:83]
	v_mfma_f32_16x16x32_bf16 v[84:87], v[140:143], v[120:123], v[84:87]
	v_mfma_f32_16x16x32_bf16 v[88:91], v[144:147], v[120:123], v[88:91]
	v_mfma_f32_16x16x32_bf16 v[22:25], v[148:151], v[120:123], v[22:25]
	v_mfma_f32_16x16x32_bf16 v[40:43], v[136:139], v[124:127], v[42:45]
	v_mfma_f32_16x16x32_bf16 v[50:53], v[140:143], v[124:127], v[50:53]
	v_mfma_f32_16x16x32_bf16 v[68:71], v[144:147], v[124:127], v[68:71]
	v_mfma_f32_16x16x32_bf16 v[54:57], v[148:151], v[124:127], v[54:57]
	v_mfma_f32_16x16x32_bf16 v[44:47], v[136:139], v[128:131], v[46:49]
	v_mfma_f32_16x16x32_bf16 v[72:75], v[140:143], v[128:131], v[72:75]
	v_mfma_f32_16x16x32_bf16 v[92:95], v[144:147], v[128:131], v[92:95]
	v_mfma_f32_16x16x32_bf16 v[58:61], v[148:151], v[128:131], v[58:61]
	v_mfma_f32_16x16x32_bf16 v[34:37], v[136:139], v[132:135], v[36:39]
	v_mfma_f32_16x16x32_bf16 v[30:33], v[140:143], v[132:135], v[30:33]
	v_mfma_f32_16x16x32_bf16 v[26:29], v[144:147], v[132:135], v[26:29]
	v_mfma_f32_16x16x32_bf16 v[18:21], v[148:151], v[132:135], v[18:21]
	s_waitcnt vmcnt(6) lgkmcnt(0)
	s_barrier
	ds_read_b128 v[120:123], v8 offset:49152
	ds_read_b128 v[124:127], v8 offset:51200
	ds_read_b128 v[128:131], v8 offset:53248
	ds_read_b128 v[132:135], v8 offset:55296
	ds_read_b128 v[136:139], v12
	ds_read_b128 v[140:143], v12 offset:2048
	ds_read_b128 v[144:147], v12 offset:4096
	ds_read_b128 v[148:151], v12 offset:6144
	v_mfma_f32_16x16x32_bf16 v[80:83], v[104:107], v[62:65], v[80:83]
	v_mfma_f32_16x16x32_bf16 v[84:87], v[108:111], v[62:65], v[84:87]
	v_mfma_f32_16x16x32_bf16 v[88:91], v[112:115], v[62:65], v[88:91]
	v_mfma_f32_16x16x32_bf16 v[22:25], v[116:119], v[62:65], v[22:25]
	v_mfma_f32_16x16x32_bf16 v[38:41], v[104:107], v[76:79], v[40:43]
	v_mfma_f32_16x16x32_bf16 v[48:51], v[108:111], v[76:79], v[50:53]
	v_mfma_f32_16x16x32_bf16 v[62:65], v[112:115], v[76:79], v[68:71]
	v_mfma_f32_16x16x32_bf16 v[52:55], v[116:119], v[76:79], v[54:57]
	v_mfma_f32_16x16x32_bf16 v[42:45], v[104:107], v[96:99], v[44:47]
	v_mfma_f32_16x16x32_bf16 v[68:71], v[108:111], v[96:99], v[72:75]
	v_mfma_f32_16x16x32_bf16 v[72:75], v[112:115], v[96:99], v[92:95]
	v_mfma_f32_16x16x32_bf16 v[56:59], v[116:119], v[96:99], v[58:61]
	v_mfma_f32_16x16x32_bf16 v[34:37], v[104:107], v[100:103], v[34:37]
	v_mfma_f32_16x16x32_bf16 v[30:33], v[108:111], v[100:103], v[30:33]
	v_mfma_f32_16x16x32_bf16 v[26:29], v[112:115], v[100:103], v[26:29]
	v_mfma_f32_16x16x32_bf16 v[18:21], v[116:119], v[100:103], v[18:21]
	s_mov_b32 m0, s61
	v_lshl_add_u64 v[46:47], v[4:5], 0, s[14:15]
	global_load_lds_dwordx4 v[46:47], off
	v_lshl_add_u64 v[46:47], v[6:7], 0, s[14:15]
	s_mov_b32 m0, s47
	s_mov_b64 s[74:75], 0x20300
	global_load_lds_dwordx4 v[46:47], off
	v_lshl_add_u64 v[46:47], v[2:3], 0, s[14:15]
	s_mov_b32 m0, s60
	s_nop 0
	global_load_lds_dwordx4 v[46:47], off
	v_lshl_add_u64 v[46:47], v[2:3], 0, s[74:75]
	s_mov_b32 m0, s33
	s_mov_b64 s[74:75], 0x40300
	global_load_lds_dwordx4 v[46:47], off
	v_lshl_add_u64 v[46:47], v[2:3], 0, s[74:75]
	s_mov_b32 m0, s5
	s_mov_b64 s[74:75], 0x60300
	global_load_lds_dwordx4 v[46:47], off
	v_lshl_add_u64 v[46:47], v[2:3], 0, s[74:75]
	s_mov_b32 m0, s2
	s_nop 0
	global_load_lds_dwordx4 v[46:47], off
	ds_read_b128 v[76:79], v10 offset:49152
	ds_read_b128 v[92:95], v10 offset:51200
	ds_read_b128 v[96:99], v10 offset:53248
	ds_read_b128 v[100:103], v10 offset:55296
	ds_read_b128 v[104:107], v13
	ds_read_b128 v[108:111], v13 offset:2048
	ds_read_b128 v[112:115], v13 offset:4096
	ds_read_b128 v[116:119], v13 offset:6144
	s_waitcnt lgkmcnt(8)
	v_mfma_f32_16x16x32_bf16 v[80:83], v[136:139], v[120:123], v[80:83]
	v_mfma_f32_16x16x32_bf16 v[84:87], v[140:143], v[120:123], v[84:87]
	v_mfma_f32_16x16x32_bf16 v[88:91], v[144:147], v[120:123], v[88:91]
	v_mfma_f32_16x16x32_bf16 v[22:25], v[148:151], v[120:123], v[22:25]
	v_mfma_f32_16x16x32_bf16 v[38:41], v[136:139], v[124:127], v[38:41]
	v_mfma_f32_16x16x32_bf16 v[46:49], v[140:143], v[124:127], v[48:51]
	v_mfma_f32_16x16x32_bf16 v[60:63], v[144:147], v[124:127], v[62:65]
	v_mfma_f32_16x16x32_bf16 v[50:53], v[148:151], v[124:127], v[52:55]
	v_mfma_f32_16x16x32_bf16 v[42:45], v[136:139], v[128:131], v[42:45]
	v_mfma_f32_16x16x32_bf16 v[68:71], v[140:143], v[128:131], v[68:71]
	v_mfma_f32_16x16x32_bf16 v[72:75], v[144:147], v[128:131], v[72:75]
	v_mfma_f32_16x16x32_bf16 v[54:57], v[148:151], v[128:131], v[56:59]
	v_mfma_f32_16x16x32_bf16 v[34:37], v[136:139], v[132:135], v[34:37]
	v_mfma_f32_16x16x32_bf16 v[30:33], v[140:143], v[132:135], v[30:33]
	v_mfma_f32_16x16x32_bf16 v[26:29], v[144:147], v[132:135], v[26:29]
	v_mfma_f32_16x16x32_bf16 v[18:21], v[148:151], v[132:135], v[18:21]
	s_waitcnt vmcnt(6) lgkmcnt(0)
	s_barrier
	ds_read_b128 v[120:123], v14
	ds_read_b128 v[124:127], v14 offset:2048
	ds_read_b128 v[128:131], v14 offset:4096
	ds_read_b128 v[132:135], v14 offset:6144
	ds_read_b128 v[136:139], v15
	ds_read_b128 v[140:143], v15 offset:2048
	ds_read_b128 v[144:147], v15 offset:4096
	ds_read_b128 v[148:151], v15 offset:6144
	v_mfma_f32_16x16x32_bf16 v[80:83], v[104:107], v[76:79], v[80:83]
	v_mfma_f32_16x16x32_bf16 v[84:87], v[108:111], v[76:79], v[84:87]
	v_mfma_f32_16x16x32_bf16 v[88:91], v[112:115], v[76:79], v[88:91]
	v_mfma_f32_16x16x32_bf16 v[22:25], v[116:119], v[76:79], v[22:25]
	v_mfma_f32_16x16x32_bf16 v[38:41], v[104:107], v[92:95], v[38:41]
	v_mfma_f32_16x16x32_bf16 v[46:49], v[108:111], v[92:95], v[46:49]
	v_mfma_f32_16x16x32_bf16 v[58:61], v[112:115], v[92:95], v[60:63]
	v_mfma_f32_16x16x32_bf16 v[50:53], v[116:119], v[92:95], v[50:53]
	v_mfma_f32_16x16x32_bf16 v[42:45], v[104:107], v[96:99], v[42:45]
	v_mfma_f32_16x16x32_bf16 v[62:65], v[108:111], v[96:99], v[68:71]
	v_mfma_f32_16x16x32_bf16 v[68:71], v[112:115], v[96:99], v[72:75]
	v_mfma_f32_16x16x32_bf16 v[54:57], v[116:119], v[96:99], v[54:57]
	v_mfma_f32_16x16x32_bf16 v[34:37], v[104:107], v[100:103], v[34:37]
	v_mfma_f32_16x16x32_bf16 v[30:33], v[108:111], v[100:103], v[30:33]
	v_mfma_f32_16x16x32_bf16 v[26:29], v[112:115], v[100:103], v[26:29]
	v_mfma_f32_16x16x32_bf16 v[18:21], v[116:119], v[100:103], v[18:21]
	s_mov_b32 m0, s63
	v_lshl_add_u64 v[72:73], v[4:5], 0, s[16:17]
	global_load_lds_dwordx4 v[72:73], off
	v_lshl_add_u64 v[72:73], v[6:7], 0, s[16:17]
	s_mov_b32 m0, s62
	s_mov_b64 s[74:75], 0x20380
	global_load_lds_dwordx4 v[72:73], off
	v_lshl_add_u64 v[72:73], v[2:3], 0, s[16:17]
	s_mov_b32 m0, s64
	s_nop 0
	global_load_lds_dwordx4 v[72:73], off
	v_lshl_add_u64 v[72:73], v[2:3], 0, s[74:75]
	s_mov_b32 m0, s65
	s_mov_b64 s[74:75], 0x40380
	global_load_lds_dwordx4 v[72:73], off
	v_lshl_add_u64 v[72:73], v[2:3], 0, s[74:75]
	s_mov_b32 m0, s66
	s_mov_b64 s[74:75], 0x60380
	global_load_lds_dwordx4 v[72:73], off
	v_lshl_add_u64 v[72:73], v[2:3], 0, s[74:75]
	s_mov_b32 m0, s67
	s_nop 0
	global_load_lds_dwordx4 v[72:73], off
	ds_read_b128 v[72:75], v16
	ds_read_b128 v[76:79], v16 offset:2048
	ds_read_b128 v[92:95], v16 offset:4096
	ds_read_b128 v[96:99], v16 offset:6144
	ds_read_b128 v[100:103], v17
	ds_read_b128 v[104:107], v17 offset:2048
	ds_read_b128 v[108:111], v17 offset:4096
	ds_read_b128 v[112:115], v17 offset:6144
	s_waitcnt lgkmcnt(8)
	v_mfma_f32_16x16x32_bf16 v[80:83], v[136:139], v[120:123], v[80:83]
	v_mfma_f32_16x16x32_bf16 v[84:87], v[140:143], v[120:123], v[84:87]
	v_mfma_f32_16x16x32_bf16 v[88:91], v[144:147], v[120:123], v[88:91]
	v_mfma_f32_16x16x32_bf16 v[22:25], v[148:151], v[120:123], v[22:25]
	v_mfma_f32_16x16x32_bf16 v[38:41], v[136:139], v[124:127], v[38:41]
	v_mfma_f32_16x16x32_bf16 v[46:49], v[140:143], v[124:127], v[46:49]
	v_mfma_f32_16x16x32_bf16 v[58:61], v[144:147], v[124:127], v[58:61]
	v_mfma_f32_16x16x32_bf16 v[50:53], v[148:151], v[124:127], v[50:53]
	v_mfma_f32_16x16x32_bf16 v[42:45], v[136:139], v[128:131], v[42:45]
	v_mfma_f32_16x16x32_bf16 v[62:65], v[140:143], v[128:131], v[62:65]
	v_mfma_f32_16x16x32_bf16 v[68:71], v[144:147], v[128:131], v[68:71]
	v_mfma_f32_16x16x32_bf16 v[54:57], v[148:151], v[128:131], v[54:57]
	v_mfma_f32_16x16x32_bf16 v[34:37], v[136:139], v[132:135], v[34:37]
	v_mfma_f32_16x16x32_bf16 v[30:33], v[140:143], v[132:135], v[30:33]
	v_mfma_f32_16x16x32_bf16 v[26:29], v[144:147], v[132:135], v[26:29]
	v_mfma_f32_16x16x32_bf16 v[18:21], v[148:151], v[132:135], v[18:21]
	s_waitcnt vmcnt(6) lgkmcnt(0)
	s_barrier
	ds_read_b128 v[116:119], v8
	ds_read_b128 v[120:123], v8 offset:2048
	ds_read_b128 v[124:127], v8 offset:4096
	ds_read_b128 v[128:131], v8 offset:6144
	ds_read_b128 v[132:135], v9 offset:16384
	ds_read_b128 v[136:139], v9 offset:18432
	ds_read_b128 v[140:143], v9 offset:20480
	ds_read_b128 v[144:147], v9 offset:22528
	v_mfma_f32_16x16x32_bf16 v[80:83], v[100:103], v[72:75], v[80:83]
	v_mfma_f32_16x16x32_bf16 v[84:87], v[104:107], v[72:75], v[84:87]
	v_mfma_f32_16x16x32_bf16 v[88:91], v[108:111], v[72:75], v[88:91]
	v_mfma_f32_16x16x32_bf16 v[22:25], v[112:115], v[72:75], v[22:25]
	v_mfma_f32_16x16x32_bf16 v[38:41], v[100:103], v[76:79], v[38:41]
	v_mfma_f32_16x16x32_bf16 v[46:49], v[104:107], v[76:79], v[46:49]
	v_mfma_f32_16x16x32_bf16 v[58:61], v[108:111], v[76:79], v[58:61]
	v_mfma_f32_16x16x32_bf16 v[50:53], v[112:115], v[76:79], v[50:53]
	v_mfma_f32_16x16x32_bf16 v[42:45], v[100:103], v[92:95], v[42:45]
	v_mfma_f32_16x16x32_bf16 v[62:65], v[104:107], v[92:95], v[62:65]
	v_mfma_f32_16x16x32_bf16 v[68:71], v[108:111], v[92:95], v[68:71]
	v_mfma_f32_16x16x32_bf16 v[54:57], v[112:115], v[92:95], v[54:57]
	v_mfma_f32_16x16x32_bf16 v[34:37], v[100:103], v[96:99], v[34:37]
	v_mfma_f32_16x16x32_bf16 v[30:33], v[104:107], v[96:99], v[30:33]
	v_mfma_f32_16x16x32_bf16 v[26:29], v[108:111], v[96:99], v[26:29]
	v_mfma_f32_16x16x32_bf16 v[18:21], v[112:115], v[96:99], v[18:21]
	s_mov_b32 m0, s68
	v_lshl_add_u64 v[72:73], v[4:5], 0, s[18:19]
	global_load_lds_dwordx4 v[72:73], off
	v_lshl_add_u64 v[72:73], v[6:7], 0, s[18:19]
	s_mov_b32 m0, s69
	s_mov_b64 s[74:75], 0x20400
	global_load_lds_dwordx4 v[72:73], off
	v_lshl_add_u64 v[72:73], v[2:3], 0, s[18:19]
	s_mov_b32 m0, s70
	s_nop 0
	global_load_lds_dwordx4 v[72:73], off
	v_lshl_add_u64 v[72:73], v[2:3], 0, s[74:75]
	s_mov_b32 m0, s71
	s_mov_b64 s[74:75], 0x40400
	global_load_lds_dwordx4 v[72:73], off
	v_lshl_add_u64 v[72:73], v[2:3], 0, s[74:75]
	s_mov_b32 m0, s72
	s_mov_b64 s[74:75], 0x60400
	global_load_lds_dwordx4 v[72:73], off
	v_lshl_add_u64 v[72:73], v[2:3], 0, s[74:75]
	s_mov_b32 m0, s73
	s_nop 0
	global_load_lds_dwordx4 v[72:73], off
	ds_read_b128 v[72:75], v10
	ds_read_b128 v[76:79], v10 offset:2048
	ds_read_b128 v[92:95], v10 offset:4096
	ds_read_b128 v[96:99], v10 offset:6144
	ds_read_b128 v[100:103], v11 offset:16384
	ds_read_b128 v[104:107], v11 offset:18432
	ds_read_b128 v[108:111], v11 offset:20480
	ds_read_b128 v[112:115], v11 offset:22528
	s_waitcnt lgkmcnt(8)
	v_mfma_f32_16x16x32_bf16 v[80:83], v[132:135], v[116:119], v[80:83]
	v_mfma_f32_16x16x32_bf16 v[84:87], v[136:139], v[116:119], v[84:87]
	v_mfma_f32_16x16x32_bf16 v[88:91], v[140:143], v[116:119], v[88:91]
	v_mfma_f32_16x16x32_bf16 v[22:25], v[144:147], v[116:119], v[22:25]
	v_mfma_f32_16x16x32_bf16 v[38:41], v[132:135], v[120:123], v[38:41]
	v_mfma_f32_16x16x32_bf16 v[46:49], v[136:139], v[120:123], v[46:49]
	v_mfma_f32_16x16x32_bf16 v[58:61], v[140:143], v[120:123], v[58:61]
	v_mfma_f32_16x16x32_bf16 v[50:53], v[144:147], v[120:123], v[50:53]
	v_mfma_f32_16x16x32_bf16 v[42:45], v[132:135], v[124:127], v[42:45]
	v_mfma_f32_16x16x32_bf16 v[62:65], v[136:139], v[124:127], v[62:65]
	v_mfma_f32_16x16x32_bf16 v[68:71], v[140:143], v[124:127], v[68:71]
	v_mfma_f32_16x16x32_bf16 v[54:57], v[144:147], v[124:127], v[54:57]
	v_mfma_f32_16x16x32_bf16 v[34:37], v[132:135], v[128:131], v[34:37]
	v_mfma_f32_16x16x32_bf16 v[30:33], v[136:139], v[128:131], v[30:33]
	v_mfma_f32_16x16x32_bf16 v[26:29], v[140:143], v[128:131], v[26:29]
	v_mfma_f32_16x16x32_bf16 v[18:21], v[144:147], v[128:131], v[18:21]
	s_waitcnt vmcnt(6) lgkmcnt(0)
	s_barrier
	ds_read_b128 v[116:119], v8 offset:49152
	ds_read_b128 v[120:123], v8 offset:51200
	ds_read_b128 v[124:127], v8 offset:53248
	ds_read_b128 v[128:131], v8 offset:55296
	ds_read_b128 v[132:135], v12
	ds_read_b128 v[136:139], v12 offset:2048
	ds_read_b128 v[140:143], v12 offset:4096
	ds_read_b128 v[144:147], v12 offset:6144
	v_mfma_f32_16x16x32_bf16 v[80:83], v[100:103], v[72:75], v[80:83]
	v_mfma_f32_16x16x32_bf16 v[84:87], v[104:107], v[72:75], v[84:87]
	v_mfma_f32_16x16x32_bf16 v[88:91], v[108:111], v[72:75], v[88:91]
	v_mfma_f32_16x16x32_bf16 v[22:25], v[112:115], v[72:75], v[22:25]
	v_mfma_f32_16x16x32_bf16 v[38:41], v[100:103], v[76:79], v[38:41]
	v_mfma_f32_16x16x32_bf16 v[46:49], v[104:107], v[76:79], v[46:49]
	v_mfma_f32_16x16x32_bf16 v[58:61], v[108:111], v[76:79], v[58:61]
	v_mfma_f32_16x16x32_bf16 v[50:53], v[112:115], v[76:79], v[50:53]
	v_mfma_f32_16x16x32_bf16 v[42:45], v[100:103], v[92:95], v[42:45]
	v_mfma_f32_16x16x32_bf16 v[62:65], v[104:107], v[92:95], v[62:65]
	v_mfma_f32_16x16x32_bf16 v[68:71], v[108:111], v[92:95], v[68:71]
	v_mfma_f32_16x16x32_bf16 v[54:57], v[112:115], v[92:95], v[54:57]
	v_mfma_f32_16x16x32_bf16 v[34:37], v[100:103], v[96:99], v[34:37]
	v_mfma_f32_16x16x32_bf16 v[30:33], v[104:107], v[96:99], v[30:33]
	v_mfma_f32_16x16x32_bf16 v[26:29], v[108:111], v[96:99], v[26:29]
	v_mfma_f32_16x16x32_bf16 v[18:21], v[112:115], v[96:99], v[18:21]
	s_mov_b32 m0, s61
	v_lshl_add_u64 v[72:73], v[4:5], 0, s[20:21]
	global_load_lds_dwordx4 v[72:73], off
	v_lshl_add_u64 v[72:73], v[6:7], 0, s[20:21]
	s_mov_b32 m0, s47
	s_mov_b64 s[74:75], 0x20480
	global_load_lds_dwordx4 v[72:73], off
	v_lshl_add_u64 v[72:73], v[2:3], 0, s[20:21]
	s_mov_b32 m0, s60
	s_nop 0
	global_load_lds_dwordx4 v[72:73], off
	v_lshl_add_u64 v[72:73], v[2:3], 0, s[74:75]
	s_mov_b32 m0, s33
	s_mov_b64 s[74:75], 0x40480
	global_load_lds_dwordx4 v[72:73], off
	v_lshl_add_u64 v[72:73], v[2:3], 0, s[74:75]
	s_mov_b32 m0, s5
	s_mov_b64 s[74:75], 0x60480
	global_load_lds_dwordx4 v[72:73], off
	v_lshl_add_u64 v[72:73], v[2:3], 0, s[74:75]
	s_mov_b32 m0, s2
	s_nop 0
	global_load_lds_dwordx4 v[72:73], off
	ds_read_b128 v[72:75], v10 offset:49152
	ds_read_b128 v[76:79], v10 offset:51200
	ds_read_b128 v[92:95], v10 offset:53248
	ds_read_b128 v[96:99], v10 offset:55296
	ds_read_b128 v[100:103], v13
	ds_read_b128 v[104:107], v13 offset:2048
	ds_read_b128 v[108:111], v13 offset:4096
	ds_read_b128 v[112:115], v13 offset:6144
	s_waitcnt lgkmcnt(8)
	v_mfma_f32_16x16x32_bf16 v[80:83], v[132:135], v[116:119], v[80:83]
	v_mfma_f32_16x16x32_bf16 v[84:87], v[136:139], v[116:119], v[84:87]
	v_mfma_f32_16x16x32_bf16 v[88:91], v[140:143], v[116:119], v[88:91]
	v_mfma_f32_16x16x32_bf16 v[22:25], v[144:147], v[116:119], v[22:25]
	v_mfma_f32_16x16x32_bf16 v[38:41], v[132:135], v[120:123], v[38:41]
	v_mfma_f32_16x16x32_bf16 v[46:49], v[136:139], v[120:123], v[46:49]
	v_mfma_f32_16x16x32_bf16 v[58:61], v[140:143], v[120:123], v[58:61]
	v_mfma_f32_16x16x32_bf16 v[50:53], v[144:147], v[120:123], v[50:53]
	v_mfma_f32_16x16x32_bf16 v[42:45], v[132:135], v[124:127], v[42:45]
	v_mfma_f32_16x16x32_bf16 v[62:65], v[136:139], v[124:127], v[62:65]
	v_mfma_f32_16x16x32_bf16 v[68:71], v[140:143], v[124:127], v[68:71]
	v_mfma_f32_16x16x32_bf16 v[54:57], v[144:147], v[124:127], v[54:57]
	v_mfma_f32_16x16x32_bf16 v[34:37], v[132:135], v[128:131], v[34:37]
	v_mfma_f32_16x16x32_bf16 v[30:33], v[136:139], v[128:131], v[30:33]
	v_mfma_f32_16x16x32_bf16 v[26:29], v[140:143], v[128:131], v[26:29]
	v_mfma_f32_16x16x32_bf16 v[18:21], v[144:147], v[128:131], v[18:21]
	s_waitcnt vmcnt(6) lgkmcnt(0)
	s_barrier
	ds_read_b128 v[116:119], v14
	ds_read_b128 v[120:123], v14 offset:2048
	ds_read_b128 v[124:127], v14 offset:4096
	ds_read_b128 v[128:131], v14 offset:6144
	ds_read_b128 v[132:135], v15
	ds_read_b128 v[136:139], v15 offset:2048
	ds_read_b128 v[140:143], v15 offset:4096
	ds_read_b128 v[144:147], v15 offset:6144
	v_mfma_f32_16x16x32_bf16 v[80:83], v[100:103], v[72:75], v[80:83]
	v_mfma_f32_16x16x32_bf16 v[84:87], v[104:107], v[72:75], v[84:87]
	v_mfma_f32_16x16x32_bf16 v[88:91], v[108:111], v[72:75], v[88:91]
	v_mfma_f32_16x16x32_bf16 v[22:25], v[112:115], v[72:75], v[22:25]
	v_mfma_f32_16x16x32_bf16 v[38:41], v[100:103], v[76:79], v[38:41]
	v_mfma_f32_16x16x32_bf16 v[46:49], v[104:107], v[76:79], v[46:49]
	v_mfma_f32_16x16x32_bf16 v[58:61], v[108:111], v[76:79], v[58:61]
	v_mfma_f32_16x16x32_bf16 v[50:53], v[112:115], v[76:79], v[50:53]
	v_mfma_f32_16x16x32_bf16 v[42:45], v[100:103], v[92:95], v[42:45]
	v_mfma_f32_16x16x32_bf16 v[62:65], v[104:107], v[92:95], v[62:65]
	v_mfma_f32_16x16x32_bf16 v[68:71], v[108:111], v[92:95], v[68:71]
	v_mfma_f32_16x16x32_bf16 v[54:57], v[112:115], v[92:95], v[54:57]
	v_mfma_f32_16x16x32_bf16 v[34:37], v[100:103], v[96:99], v[34:37]
	v_mfma_f32_16x16x32_bf16 v[30:33], v[104:107], v[96:99], v[30:33]
	v_mfma_f32_16x16x32_bf16 v[26:29], v[108:111], v[96:99], v[26:29]
	v_mfma_f32_16x16x32_bf16 v[18:21], v[112:115], v[96:99], v[18:21]
	s_mov_b32 m0, s63
	v_lshl_add_u64 v[72:73], v[4:5], 0, s[24:25]
	global_load_lds_dwordx4 v[72:73], off
	v_lshl_add_u64 v[72:73], v[6:7], 0, s[24:25]
	s_mov_b32 m0, s62
	s_mov_b64 s[74:75], 0x20500
	global_load_lds_dwordx4 v[72:73], off
	v_lshl_add_u64 v[72:73], v[2:3], 0, s[24:25]
	s_mov_b32 m0, s64
	s_nop 0
	global_load_lds_dwordx4 v[72:73], off
	v_lshl_add_u64 v[72:73], v[2:3], 0, s[74:75]
	s_mov_b32 m0, s65
	s_mov_b64 s[74:75], 0x40500
	global_load_lds_dwordx4 v[72:73], off
	v_lshl_add_u64 v[72:73], v[2:3], 0, s[74:75]
	s_mov_b32 m0, s66
	s_mov_b64 s[74:75], 0x60500
	global_load_lds_dwordx4 v[72:73], off
	v_lshl_add_u64 v[72:73], v[2:3], 0, s[74:75]
	s_mov_b32 m0, s67
	s_nop 0
	global_load_lds_dwordx4 v[72:73], off
	ds_read_b128 v[72:75], v16
	ds_read_b128 v[76:79], v16 offset:2048
	ds_read_b128 v[92:95], v16 offset:4096
	ds_read_b128 v[96:99], v16 offset:6144
	ds_read_b128 v[100:103], v17
	ds_read_b128 v[104:107], v17 offset:2048
	ds_read_b128 v[108:111], v17 offset:4096
	ds_read_b128 v[112:115], v17 offset:6144
	s_waitcnt lgkmcnt(8)
	v_mfma_f32_16x16x32_bf16 v[80:83], v[132:135], v[116:119], v[80:83]
	v_mfma_f32_16x16x32_bf16 v[84:87], v[136:139], v[116:119], v[84:87]
	v_mfma_f32_16x16x32_bf16 v[88:91], v[140:143], v[116:119], v[88:91]
	v_mfma_f32_16x16x32_bf16 v[22:25], v[144:147], v[116:119], v[22:25]
	v_mfma_f32_16x16x32_bf16 v[38:41], v[132:135], v[120:123], v[38:41]
	v_mfma_f32_16x16x32_bf16 v[46:49], v[136:139], v[120:123], v[46:49]
	v_mfma_f32_16x16x32_bf16 v[58:61], v[140:143], v[120:123], v[58:61]
	v_mfma_f32_16x16x32_bf16 v[50:53], v[144:147], v[120:123], v[50:53]
	v_mfma_f32_16x16x32_bf16 v[42:45], v[132:135], v[124:127], v[42:45]
	v_mfma_f32_16x16x32_bf16 v[62:65], v[136:139], v[124:127], v[62:65]
	v_mfma_f32_16x16x32_bf16 v[68:71], v[140:143], v[124:127], v[68:71]
	v_mfma_f32_16x16x32_bf16 v[54:57], v[144:147], v[124:127], v[54:57]
	v_mfma_f32_16x16x32_bf16 v[34:37], v[132:135], v[128:131], v[34:37]
	v_mfma_f32_16x16x32_bf16 v[30:33], v[136:139], v[128:131], v[30:33]
	v_mfma_f32_16x16x32_bf16 v[26:29], v[140:143], v[128:131], v[26:29]
	v_mfma_f32_16x16x32_bf16 v[18:21], v[144:147], v[128:131], v[18:21]
	s_waitcnt vmcnt(6) lgkmcnt(0)
	s_barrier
	ds_read_b128 v[116:119], v8
	ds_read_b128 v[120:123], v8 offset:2048
	ds_read_b128 v[124:127], v8 offset:4096
	ds_read_b128 v[128:131], v8 offset:6144
	ds_read_b128 v[132:135], v9 offset:16384
	ds_read_b128 v[136:139], v9 offset:18432
	ds_read_b128 v[140:143], v9 offset:20480
	ds_read_b128 v[144:147], v9 offset:22528
	v_mfma_f32_16x16x32_bf16 v[80:83], v[100:103], v[72:75], v[80:83]
	v_mfma_f32_16x16x32_bf16 v[84:87], v[104:107], v[72:75], v[84:87]
	v_mfma_f32_16x16x32_bf16 v[88:91], v[108:111], v[72:75], v[88:91]
	v_mfma_f32_16x16x32_bf16 v[22:25], v[112:115], v[72:75], v[22:25]
	v_mfma_f32_16x16x32_bf16 v[38:41], v[100:103], v[76:79], v[38:41]
	v_mfma_f32_16x16x32_bf16 v[46:49], v[104:107], v[76:79], v[46:49]
	v_mfma_f32_16x16x32_bf16 v[58:61], v[108:111], v[76:79], v[58:61]
	v_mfma_f32_16x16x32_bf16 v[50:53], v[112:115], v[76:79], v[50:53]
	v_mfma_f32_16x16x32_bf16 v[42:45], v[100:103], v[92:95], v[42:45]
	v_mfma_f32_16x16x32_bf16 v[62:65], v[104:107], v[92:95], v[62:65]
	v_mfma_f32_16x16x32_bf16 v[68:71], v[108:111], v[92:95], v[68:71]
	v_mfma_f32_16x16x32_bf16 v[54:57], v[112:115], v[92:95], v[54:57]
	v_mfma_f32_16x16x32_bf16 v[34:37], v[100:103], v[96:99], v[34:37]
	v_mfma_f32_16x16x32_bf16 v[30:33], v[104:107], v[96:99], v[30:33]
	v_mfma_f32_16x16x32_bf16 v[26:29], v[108:111], v[96:99], v[26:29]
	v_mfma_f32_16x16x32_bf16 v[18:21], v[112:115], v[96:99], v[18:21]
	s_mov_b32 m0, s68
	v_lshl_add_u64 v[72:73], v[4:5], 0, s[26:27]
	global_load_lds_dwordx4 v[72:73], off
	v_lshl_add_u64 v[72:73], v[6:7], 0, s[26:27]
	s_mov_b32 m0, s69
	s_mov_b64 s[74:75], 0x20580
	global_load_lds_dwordx4 v[72:73], off
	v_lshl_add_u64 v[72:73], v[2:3], 0, s[26:27]
	s_mov_b32 m0, s70
	s_nop 0
	global_load_lds_dwordx4 v[72:73], off
	v_lshl_add_u64 v[72:73], v[2:3], 0, s[74:75]
	s_mov_b32 m0, s71
	s_mov_b64 s[74:75], 0x40580
	global_load_lds_dwordx4 v[72:73], off
	v_lshl_add_u64 v[72:73], v[2:3], 0, s[74:75]
	s_mov_b32 m0, s72
	s_mov_b64 s[74:75], 0x60580
	global_load_lds_dwordx4 v[72:73], off
	v_lshl_add_u64 v[72:73], v[2:3], 0, s[74:75]
	s_mov_b32 m0, s73
	s_nop 0
	global_load_lds_dwordx4 v[72:73], off
	ds_read_b128 v[72:75], v10
	ds_read_b128 v[76:79], v10 offset:2048
	ds_read_b128 v[92:95], v10 offset:4096
	ds_read_b128 v[96:99], v10 offset:6144
	ds_read_b128 v[100:103], v11 offset:16384
	ds_read_b128 v[104:107], v11 offset:18432
	ds_read_b128 v[108:111], v11 offset:20480
	ds_read_b128 v[112:115], v11 offset:22528
	s_waitcnt lgkmcnt(8)
	v_mfma_f32_16x16x32_bf16 v[80:83], v[132:135], v[116:119], v[80:83]
	v_mfma_f32_16x16x32_bf16 v[84:87], v[136:139], v[116:119], v[84:87]
	v_mfma_f32_16x16x32_bf16 v[88:91], v[140:143], v[116:119], v[88:91]
	v_mfma_f32_16x16x32_bf16 v[22:25], v[144:147], v[116:119], v[22:25]
	v_mfma_f32_16x16x32_bf16 v[38:41], v[132:135], v[120:123], v[38:41]
	v_mfma_f32_16x16x32_bf16 v[46:49], v[136:139], v[120:123], v[46:49]
	v_mfma_f32_16x16x32_bf16 v[58:61], v[140:143], v[120:123], v[58:61]
	v_mfma_f32_16x16x32_bf16 v[50:53], v[144:147], v[120:123], v[50:53]
	v_mfma_f32_16x16x32_bf16 v[42:45], v[132:135], v[124:127], v[42:45]
	v_mfma_f32_16x16x32_bf16 v[62:65], v[136:139], v[124:127], v[62:65]
	v_mfma_f32_16x16x32_bf16 v[68:71], v[140:143], v[124:127], v[68:71]
	v_mfma_f32_16x16x32_bf16 v[54:57], v[144:147], v[124:127], v[54:57]
	v_mfma_f32_16x16x32_bf16 v[34:37], v[132:135], v[128:131], v[34:37]
	v_mfma_f32_16x16x32_bf16 v[30:33], v[136:139], v[128:131], v[30:33]
	v_mfma_f32_16x16x32_bf16 v[26:29], v[140:143], v[128:131], v[26:29]
	v_mfma_f32_16x16x32_bf16 v[18:21], v[144:147], v[128:131], v[18:21]
	s_waitcnt vmcnt(6) lgkmcnt(0)
	s_barrier
	ds_read_b128 v[116:119], v8 offset:49152
	ds_read_b128 v[120:123], v8 offset:51200
	ds_read_b128 v[124:127], v8 offset:53248
	ds_read_b128 v[128:131], v8 offset:55296
	ds_read_b128 v[132:135], v12
	ds_read_b128 v[136:139], v12 offset:2048
	ds_read_b128 v[140:143], v12 offset:4096
	ds_read_b128 v[144:147], v12 offset:6144
	v_mfma_f32_16x16x32_bf16 v[80:83], v[100:103], v[72:75], v[80:83]
	v_mfma_f32_16x16x32_bf16 v[84:87], v[104:107], v[72:75], v[84:87]
	v_mfma_f32_16x16x32_bf16 v[88:91], v[108:111], v[72:75], v[88:91]
	v_mfma_f32_16x16x32_bf16 v[22:25], v[112:115], v[72:75], v[22:25]
	v_mfma_f32_16x16x32_bf16 v[38:41], v[100:103], v[76:79], v[38:41]
	v_mfma_f32_16x16x32_bf16 v[46:49], v[104:107], v[76:79], v[46:49]
	v_mfma_f32_16x16x32_bf16 v[58:61], v[108:111], v[76:79], v[58:61]
	v_mfma_f32_16x16x32_bf16 v[50:53], v[112:115], v[76:79], v[50:53]
	v_mfma_f32_16x16x32_bf16 v[42:45], v[100:103], v[92:95], v[42:45]
	v_mfma_f32_16x16x32_bf16 v[62:65], v[104:107], v[92:95], v[62:65]
	v_mfma_f32_16x16x32_bf16 v[68:71], v[108:111], v[92:95], v[68:71]
	v_mfma_f32_16x16x32_bf16 v[54:57], v[112:115], v[92:95], v[54:57]
	v_mfma_f32_16x16x32_bf16 v[34:37], v[100:103], v[96:99], v[34:37]
	v_mfma_f32_16x16x32_bf16 v[30:33], v[104:107], v[96:99], v[30:33]
	v_mfma_f32_16x16x32_bf16 v[26:29], v[108:111], v[96:99], v[26:29]
	v_mfma_f32_16x16x32_bf16 v[18:21], v[112:115], v[96:99], v[18:21]
	s_mov_b32 m0, s61
	v_lshl_add_u64 v[72:73], v[4:5], 0, s[28:29]
	global_load_lds_dwordx4 v[72:73], off
	v_lshl_add_u64 v[72:73], v[6:7], 0, s[28:29]
	s_mov_b32 m0, s47
	s_mov_b64 s[74:75], 0x20600
	global_load_lds_dwordx4 v[72:73], off
	v_lshl_add_u64 v[72:73], v[2:3], 0, s[28:29]
	s_mov_b32 m0, s60
	s_nop 0
	global_load_lds_dwordx4 v[72:73], off
	v_lshl_add_u64 v[72:73], v[2:3], 0, s[74:75]
	s_mov_b32 m0, s33
	s_mov_b64 s[74:75], 0x40600
	global_load_lds_dwordx4 v[72:73], off
	v_lshl_add_u64 v[72:73], v[2:3], 0, s[74:75]
	s_mov_b32 m0, s5
	s_mov_b64 s[74:75], 0x60600
	global_load_lds_dwordx4 v[72:73], off
	v_lshl_add_u64 v[72:73], v[2:3], 0, s[74:75]
	s_mov_b32 m0, s2
	s_nop 0
	global_load_lds_dwordx4 v[72:73], off
	ds_read_b128 v[72:75], v10 offset:49152
	ds_read_b128 v[76:79], v10 offset:51200
	ds_read_b128 v[92:95], v10 offset:53248
	ds_read_b128 v[96:99], v10 offset:55296
	ds_read_b128 v[100:103], v13
	ds_read_b128 v[104:107], v13 offset:2048
	ds_read_b128 v[108:111], v13 offset:4096
	ds_read_b128 v[112:115], v13 offset:6144
	s_waitcnt lgkmcnt(8)
	v_mfma_f32_16x16x32_bf16 v[80:83], v[132:135], v[116:119], v[80:83]
	v_mfma_f32_16x16x32_bf16 v[84:87], v[136:139], v[116:119], v[84:87]
	v_mfma_f32_16x16x32_bf16 v[88:91], v[140:143], v[116:119], v[88:91]
	v_mfma_f32_16x16x32_bf16 v[22:25], v[144:147], v[116:119], v[22:25]
	v_mfma_f32_16x16x32_bf16 v[38:41], v[132:135], v[120:123], v[38:41]
	v_mfma_f32_16x16x32_bf16 v[46:49], v[136:139], v[120:123], v[46:49]
	v_mfma_f32_16x16x32_bf16 v[58:61], v[140:143], v[120:123], v[58:61]
	v_mfma_f32_16x16x32_bf16 v[50:53], v[144:147], v[120:123], v[50:53]
	v_mfma_f32_16x16x32_bf16 v[42:45], v[132:135], v[124:127], v[42:45]
	v_mfma_f32_16x16x32_bf16 v[62:65], v[136:139], v[124:127], v[62:65]
	v_mfma_f32_16x16x32_bf16 v[68:71], v[140:143], v[124:127], v[68:71]
	v_mfma_f32_16x16x32_bf16 v[54:57], v[144:147], v[124:127], v[54:57]
	v_mfma_f32_16x16x32_bf16 v[34:37], v[132:135], v[128:131], v[34:37]
	v_mfma_f32_16x16x32_bf16 v[30:33], v[136:139], v[128:131], v[30:33]
	v_mfma_f32_16x16x32_bf16 v[26:29], v[140:143], v[128:131], v[26:29]
	v_mfma_f32_16x16x32_bf16 v[18:21], v[144:147], v[128:131], v[18:21]
	s_waitcnt vmcnt(6) lgkmcnt(0)
	s_barrier
	s_lshr_b32 s58, s39, 7
	s_add_i32 s58, s98, s58
	s_cmpk_ge_i32 s58, 0x800
	s_cbranch_scc1 .Lpf7_p1_skip
	s_mov_b32 s74, s58
	s_cmp_lg_u32 s39, 0x8000
	s_cbranch_scc1 .Lpf7_p1_nomap
	s_lshr_b32 s75, s58, 8
	s_bfe_u32 s76, s58, 0x30005
	s_and_b32 s77, s58, 31
	s_lshr_b32 s78, s75, 2
	s_lshl_b32 s78, s78, 3
	s_add_i32 s76, s76, s78
	s_and_b32 s75, s75, 3
	s_lshr_b32 s78, s75, 1
	s_xor_b32 s75, s75, s78
	s_and_b32 s75, s75, 1
	s_lshl_b32 s78, s78, 3
	s_lshr_b32 s79, s77, 2
	s_add_i32 s78, s78, s79
	s_and_b32 s77, s77, 3
	s_lshl_b32 s75, s75, 2
	s_add_i32 s75, s75, s77
	s_lshl_b32 s76, s76, 7
	s_lshl_b32 s75, s75, 4
	s_add_i32 s76, s76, s75
	s_add_i32 s74, s76, s78
.Lpf7_p1_nomap:
	s_ashr_i32 s75, s74, 7
	s_bfe_u32 s76, s74, 0x20002
	s_lshl_b32 s76, s76, 4
	s_add_i32 s76, s76, s75
	s_lshl_b32 s76, s76, 9
	s_lshl_b32 s77, s74, 7
	s_and_b32 s77, s77, 0x180
	s_or_b32 s76, s76, s77
	v_ashrrev_i32_e32 v202, 3, v0
	v_add_u32_e32 v204, s76, v202
	v_ashrrev_i32_e32 v205, 31, v204
	v_lshl_add_u64 v[204:205], v[204:205], 2, s[52:53]
	global_load_dword v200, v[204:205], off
	global_load_dword v201, v[204:205], off offset:256
.Lpf7_p1_skip:
	ds_read_b128 v[116:119], v14
	ds_read_b128 v[120:123], v14 offset:2048
	ds_read_b128 v[124:127], v14 offset:4096
	ds_read_b128 v[128:131], v14 offset:6144
	ds_read_b128 v[132:135], v15
	ds_read_b128 v[136:139], v15 offset:2048
	ds_read_b128 v[140:143], v15 offset:4096
	ds_read_b128 v[144:147], v15 offset:6144
	v_mfma_f32_16x16x32_bf16 v[80:83], v[100:103], v[72:75], v[80:83]
	v_mfma_f32_16x16x32_bf16 v[84:87], v[104:107], v[72:75], v[84:87]
	v_mfma_f32_16x16x32_bf16 v[88:91], v[108:111], v[72:75], v[88:91]
	v_mfma_f32_16x16x32_bf16 v[22:25], v[112:115], v[72:75], v[22:25]
	v_mfma_f32_16x16x32_bf16 v[38:41], v[100:103], v[76:79], v[38:41]
	v_mfma_f32_16x16x32_bf16 v[46:49], v[104:107], v[76:79], v[46:49]
	v_mfma_f32_16x16x32_bf16 v[58:61], v[108:111], v[76:79], v[58:61]
	v_mfma_f32_16x16x32_bf16 v[50:53], v[112:115], v[76:79], v[50:53]
	v_mfma_f32_16x16x32_bf16 v[42:45], v[100:103], v[92:95], v[42:45]
	v_mfma_f32_16x16x32_bf16 v[62:65], v[104:107], v[92:95], v[62:65]
	v_mfma_f32_16x16x32_bf16 v[68:71], v[108:111], v[92:95], v[68:71]
	v_mfma_f32_16x16x32_bf16 v[54:57], v[112:115], v[92:95], v[54:57]
	v_mfma_f32_16x16x32_bf16 v[34:37], v[100:103], v[96:99], v[34:37]
	v_mfma_f32_16x16x32_bf16 v[30:33], v[104:107], v[96:99], v[30:33]
	v_mfma_f32_16x16x32_bf16 v[26:29], v[108:111], v[96:99], v[26:29]
	v_mfma_f32_16x16x32_bf16 v[18:21], v[112:115], v[96:99], v[18:21]
	s_mov_b32 m0, s63
	v_lshl_add_u64 v[72:73], v[4:5], 0, s[30:31]
	global_load_lds_dwordx4 v[72:73], off
	v_lshl_add_u64 v[72:73], v[6:7], 0, s[30:31]
	s_mov_b32 m0, s62
	s_mov_b64 s[62:63], 0x20680
	global_load_lds_dwordx4 v[72:73], off
	v_lshl_add_u64 v[72:73], v[2:3], 0, s[30:31]
	s_mov_b32 m0, s64
	s_nop 0
	global_load_lds_dwordx4 v[72:73], off
	v_lshl_add_u64 v[72:73], v[2:3], 0, s[62:63]
	s_mov_b32 m0, s65
	s_mov_b64 s[62:63], 0x40680
	global_load_lds_dwordx4 v[72:73], off
	v_lshl_add_u64 v[72:73], v[2:3], 0, s[62:63]
	s_mov_b32 m0, s66
	s_mov_b64 s[62:63], 0x60680
	global_load_lds_dwordx4 v[72:73], off
	v_lshl_add_u64 v[72:73], v[2:3], 0, s[62:63]
	s_mov_b32 m0, s67
	v_readlane_b32 s66, v196, 22
	global_load_lds_dwordx4 v[72:73], off
	ds_read_b128 v[72:75], v16
	ds_read_b128 v[76:79], v16 offset:2048
	ds_read_b128 v[92:95], v16 offset:4096
	ds_read_b128 v[96:99], v16 offset:6144
	ds_read_b128 v[100:103], v17
	ds_read_b128 v[104:107], v17 offset:2048
	ds_read_b128 v[108:111], v17 offset:4096
	ds_read_b128 v[112:115], v17 offset:6144
	v_readlane_b32 s67, v196, 23
	s_waitcnt lgkmcnt(8)
	v_mfma_f32_16x16x32_bf16 v[80:83], v[132:135], v[116:119], v[80:83]
	v_mfma_f32_16x16x32_bf16 v[84:87], v[136:139], v[116:119], v[84:87]
	v_mfma_f32_16x16x32_bf16 v[88:91], v[140:143], v[116:119], v[88:91]
	v_mfma_f32_16x16x32_bf16 v[22:25], v[144:147], v[116:119], v[22:25]
	v_mfma_f32_16x16x32_bf16 v[38:41], v[132:135], v[120:123], v[38:41]
	v_mfma_f32_16x16x32_bf16 v[46:49], v[136:139], v[120:123], v[46:49]
	v_mfma_f32_16x16x32_bf16 v[58:61], v[140:143], v[120:123], v[58:61]
	v_mfma_f32_16x16x32_bf16 v[50:53], v[144:147], v[120:123], v[50:53]
	v_mfma_f32_16x16x32_bf16 v[42:45], v[132:135], v[124:127], v[42:45]
	v_mfma_f32_16x16x32_bf16 v[62:65], v[136:139], v[124:127], v[62:65]
	v_mfma_f32_16x16x32_bf16 v[68:71], v[140:143], v[124:127], v[68:71]
	v_mfma_f32_16x16x32_bf16 v[54:57], v[144:147], v[124:127], v[54:57]
	v_mfma_f32_16x16x32_bf16 v[34:37], v[132:135], v[128:131], v[34:37]
	v_mfma_f32_16x16x32_bf16 v[30:33], v[136:139], v[128:131], v[30:33]
	v_mfma_f32_16x16x32_bf16 v[26:29], v[140:143], v[128:131], v[26:29]
	v_mfma_f32_16x16x32_bf16 v[18:21], v[144:147], v[128:131], v[18:21]
	s_waitcnt vmcnt(6) lgkmcnt(0)
	s_barrier
	ds_read_b128 v[116:119], v8
	ds_read_b128 v[120:123], v8 offset:2048
	ds_read_b128 v[124:127], v8 offset:4096
	ds_read_b128 v[128:131], v8 offset:6144
	ds_read_b128 v[132:135], v9 offset:16384
	ds_read_b128 v[136:139], v9 offset:18432
	ds_read_b128 v[140:143], v9 offset:20480
	ds_read_b128 v[144:147], v9 offset:22528
	v_mfma_f32_16x16x32_bf16 v[80:83], v[100:103], v[72:75], v[80:83]
	v_mfma_f32_16x16x32_bf16 v[84:87], v[104:107], v[72:75], v[84:87]
	v_mfma_f32_16x16x32_bf16 v[88:91], v[108:111], v[72:75], v[88:91]
	v_mfma_f32_16x16x32_bf16 v[22:25], v[112:115], v[72:75], v[22:25]
	v_mfma_f32_16x16x32_bf16 v[38:41], v[100:103], v[76:79], v[38:41]
	v_mfma_f32_16x16x32_bf16 v[46:49], v[104:107], v[76:79], v[46:49]
	v_mfma_f32_16x16x32_bf16 v[58:61], v[108:111], v[76:79], v[58:61]
	v_mfma_f32_16x16x32_bf16 v[50:53], v[112:115], v[76:79], v[50:53]
	v_mfma_f32_16x16x32_bf16 v[42:45], v[100:103], v[92:95], v[42:45]
	v_mfma_f32_16x16x32_bf16 v[62:65], v[104:107], v[92:95], v[62:65]
	v_mfma_f32_16x16x32_bf16 v[68:71], v[108:111], v[92:95], v[68:71]
	v_mfma_f32_16x16x32_bf16 v[54:57], v[112:115], v[92:95], v[54:57]
	v_mfma_f32_16x16x32_bf16 v[34:37], v[100:103], v[96:99], v[34:37]
	v_mfma_f32_16x16x32_bf16 v[30:33], v[104:107], v[96:99], v[30:33]
	v_mfma_f32_16x16x32_bf16 v[26:29], v[108:111], v[96:99], v[26:29]
	v_mfma_f32_16x16x32_bf16 v[18:21], v[112:115], v[96:99], v[18:21]
	s_mov_b32 m0, s68
	v_lshl_add_u64 v[72:73], v[4:5], 0, s[34:35]
	global_load_lds_dwordx4 v[72:73], off
	v_lshl_add_u64 v[72:73], v[6:7], 0, s[34:35]
	s_mov_b32 m0, s69
	s_mov_b64 s[62:63], 0x20700
	global_load_lds_dwordx4 v[72:73], off
	v_lshl_add_u64 v[72:73], v[2:3], 0, s[34:35]
	s_mov_b32 m0, s70
	s_nop 0
	global_load_lds_dwordx4 v[72:73], off
	v_lshl_add_u64 v[72:73], v[2:3], 0, s[62:63]
	s_mov_b32 m0, s71
	s_mov_b64 s[62:63], 0x40700
	global_load_lds_dwordx4 v[72:73], off
	v_lshl_add_u64 v[72:73], v[2:3], 0, s[62:63]
	s_mov_b32 m0, s72
	s_mov_b64 s[62:63], 0x60700
	global_load_lds_dwordx4 v[72:73], off
	v_lshl_add_u64 v[72:73], v[2:3], 0, s[62:63]
	s_mov_b32 m0, s73
	v_readlane_b32 s72, v197, 34
	global_load_lds_dwordx4 v[72:73], off
	ds_read_b128 v[72:75], v10
	ds_read_b128 v[76:79], v10 offset:2048
	ds_read_b128 v[92:95], v10 offset:4096
	ds_read_b128 v[96:99], v10 offset:6144
	ds_read_b128 v[100:103], v11 offset:16384
	ds_read_b128 v[104:107], v11 offset:18432
	ds_read_b128 v[108:111], v11 offset:20480
	ds_read_b128 v[112:115], v11 offset:22528
	v_readlane_b32 s73, v197, 35
	v_readlane_b32 s74, v197, 36
	v_readlane_b32 s75, v197, 37
	v_readlane_b32 s76, v197, 38
	v_readlane_b32 s77, v197, 39
	v_readlane_b32 s78, v197, 40
	v_readlane_b32 s79, v197, 41
	v_readlane_b32 s80, v197, 42
	v_readlane_b32 s81, v197, 43
	v_readlane_b32 s82, v197, 44
	v_readlane_b32 s83, v197, 45
	v_readlane_b32 s84, v197, 46
	v_readlane_b32 s85, v197, 47
	v_readlane_b32 s86, v197, 48
	v_readlane_b32 s87, v197, 49
	s_waitcnt lgkmcnt(8)
	v_mfma_f32_16x16x32_bf16 v[80:83], v[132:135], v[116:119], v[80:83]
	v_mfma_f32_16x16x32_bf16 v[84:87], v[136:139], v[116:119], v[84:87]
	v_mfma_f32_16x16x32_bf16 v[88:91], v[140:143], v[116:119], v[88:91]
	v_mfma_f32_16x16x32_bf16 v[22:25], v[144:147], v[116:119], v[22:25]
	v_mfma_f32_16x16x32_bf16 v[38:41], v[132:135], v[120:123], v[38:41]
	v_mfma_f32_16x16x32_bf16 v[46:49], v[136:139], v[120:123], v[46:49]
	v_mfma_f32_16x16x32_bf16 v[58:61], v[140:143], v[120:123], v[58:61]
	v_mfma_f32_16x16x32_bf16 v[50:53], v[144:147], v[120:123], v[50:53]
	v_mfma_f32_16x16x32_bf16 v[42:45], v[132:135], v[124:127], v[42:45]
	v_mfma_f32_16x16x32_bf16 v[62:65], v[136:139], v[124:127], v[62:65]
	v_mfma_f32_16x16x32_bf16 v[68:71], v[140:143], v[124:127], v[68:71]
	v_mfma_f32_16x16x32_bf16 v[54:57], v[144:147], v[124:127], v[54:57]
	v_mfma_f32_16x16x32_bf16 v[34:37], v[132:135], v[128:131], v[34:37]
	v_mfma_f32_16x16x32_bf16 v[30:33], v[136:139], v[128:131], v[30:33]
	v_mfma_f32_16x16x32_bf16 v[26:29], v[140:143], v[128:131], v[26:29]
	v_mfma_f32_16x16x32_bf16 v[18:21], v[144:147], v[128:131], v[18:21]
	s_waitcnt vmcnt(6) lgkmcnt(0)
	s_barrier
	ds_read_b128 v[116:119], v8 offset:49152
	ds_read_b128 v[120:123], v8 offset:51200
	ds_read_b128 v[124:127], v8 offset:53248
	ds_read_b128 v[128:131], v8 offset:55296
	ds_read_b128 v[132:135], v12
	ds_read_b128 v[136:139], v12 offset:2048
	ds_read_b128 v[140:143], v12 offset:4096
	ds_read_b128 v[144:147], v12 offset:6144
	v_mfma_f32_16x16x32_bf16 v[80:83], v[100:103], v[72:75], v[80:83]
	v_mfma_f32_16x16x32_bf16 v[84:87], v[104:107], v[72:75], v[84:87]
	v_mfma_f32_16x16x32_bf16 v[88:91], v[108:111], v[72:75], v[88:91]
	v_mfma_f32_16x16x32_bf16 v[22:25], v[112:115], v[72:75], v[22:25]
	v_mfma_f32_16x16x32_bf16 v[38:41], v[100:103], v[76:79], v[38:41]
	v_mfma_f32_16x16x32_bf16 v[46:49], v[104:107], v[76:79], v[46:49]
	v_mfma_f32_16x16x32_bf16 v[58:61], v[108:111], v[76:79], v[58:61]
	v_mfma_f32_16x16x32_bf16 v[50:53], v[112:115], v[76:79], v[50:53]
	v_mfma_f32_16x16x32_bf16 v[42:45], v[100:103], v[92:95], v[42:45]
	v_mfma_f32_16x16x32_bf16 v[62:65], v[104:107], v[92:95], v[62:65]
	v_mfma_f32_16x16x32_bf16 v[68:71], v[108:111], v[92:95], v[68:71]
	v_mfma_f32_16x16x32_bf16 v[54:57], v[112:115], v[92:95], v[54:57]
	v_mfma_f32_16x16x32_bf16 v[34:37], v[100:103], v[96:99], v[34:37]
	v_mfma_f32_16x16x32_bf16 v[30:33], v[104:107], v[96:99], v[30:33]
	v_mfma_f32_16x16x32_bf16 v[26:29], v[108:111], v[96:99], v[26:29]
	v_mfma_f32_16x16x32_bf16 v[18:21], v[112:115], v[96:99], v[18:21]
	s_mov_b32 m0, s61
	v_lshl_add_u64 v[4:5], v[4:5], 0, s[36:37]
	global_load_lds_dwordx4 v[4:5], off
	v_lshl_add_u64 v[4:5], v[6:7], 0, s[36:37]
	s_mov_b32 m0, s47
	s_nop 0
	global_load_lds_dwordx4 v[4:5], off
	v_lshl_add_u64 v[4:5], v[2:3], 0, s[36:37]
	s_mov_b32 m0, s60
	s_mov_b64 s[60:61], 0x20780
	global_load_lds_dwordx4 v[4:5], off
	v_lshl_add_u64 v[4:5], v[2:3], 0, s[60:61]
	s_mov_b32 m0, s33
	s_mov_b64 s[60:61], 0x40780
	global_load_lds_dwordx4 v[4:5], off
	v_lshl_add_u64 v[4:5], v[2:3], 0, s[60:61]
	s_mov_b32 m0, s5
	s_mov_b64 s[60:61], 0x60780
	global_load_lds_dwordx4 v[4:5], off
	v_lshl_add_u64 v[2:3], v[2:3], 0, s[60:61]
	s_mov_b32 m0, s2
	s_nop 0
	global_load_lds_dwordx4 v[2:3], off
	ds_read_b128 v[2:5], v10 offset:49152
	ds_read_b128 v[72:75], v10 offset:51200
	ds_read_b128 v[76:79], v10 offset:53248
	ds_read_b128 v[92:95], v10 offset:55296
	ds_read_b128 v[96:99], v13
	ds_read_b128 v[100:103], v13 offset:2048
	ds_read_b128 v[104:107], v13 offset:4096
	ds_read_b128 v[108:111], v13 offset:6144
	s_waitcnt lgkmcnt(8)
	v_mfma_f32_16x16x32_bf16 v[80:83], v[132:135], v[116:119], v[80:83]
	v_mfma_f32_16x16x32_bf16 v[84:87], v[136:139], v[116:119], v[84:87]
	v_mfma_f32_16x16x32_bf16 v[88:91], v[140:143], v[116:119], v[88:91]
	v_mfma_f32_16x16x32_bf16 v[22:25], v[144:147], v[116:119], v[22:25]
	v_mfma_f32_16x16x32_bf16 v[38:41], v[132:135], v[120:123], v[38:41]
	v_mfma_f32_16x16x32_bf16 v[46:49], v[136:139], v[120:123], v[46:49]
	v_mfma_f32_16x16x32_bf16 v[58:61], v[140:143], v[120:123], v[58:61]
	v_mfma_f32_16x16x32_bf16 v[50:53], v[144:147], v[120:123], v[50:53]
	v_mfma_f32_16x16x32_bf16 v[42:45], v[132:135], v[124:127], v[42:45]
	v_mfma_f32_16x16x32_bf16 v[62:65], v[136:139], v[124:127], v[62:65]
	v_mfma_f32_16x16x32_bf16 v[68:71], v[140:143], v[124:127], v[68:71]
	v_mfma_f32_16x16x32_bf16 v[54:57], v[144:147], v[124:127], v[54:57]
	v_mfma_f32_16x16x32_bf16 v[34:37], v[132:135], v[128:131], v[34:37]
	v_mfma_f32_16x16x32_bf16 v[30:33], v[136:139], v[128:131], v[30:33]
	v_mfma_f32_16x16x32_bf16 v[26:29], v[140:143], v[128:131], v[26:29]
	v_mfma_f32_16x16x32_bf16 v[18:21], v[144:147], v[128:131], v[18:21]
	s_waitcnt vmcnt(6) lgkmcnt(0)
	s_barrier
	ds_read_b128 v[112:115], v14
	ds_read_b128 v[116:119], v14 offset:2048
	ds_read_b128 v[120:123], v14 offset:4096
	ds_read_b128 v[124:127], v14 offset:6144
	ds_read_b128 v[128:131], v15
	ds_read_b128 v[132:135], v15 offset:2048
	ds_read_b128 v[136:139], v15 offset:4096
	ds_read_b128 v[12:15], v15 offset:6144
	v_mfma_f32_16x16x32_bf16 v[80:83], v[96:99], v[2:5], v[80:83]
	v_mfma_f32_16x16x32_bf16 v[84:87], v[100:103], v[2:5], v[84:87]
	v_mfma_f32_16x16x32_bf16 v[88:91], v[104:107], v[2:5], v[88:91]
	v_mfma_f32_16x16x32_bf16 v[2:5], v[108:111], v[2:5], v[22:25]
	v_mfma_f32_16x16x32_bf16 v[22:25], v[96:99], v[72:75], v[38:41]
	v_mfma_f32_16x16x32_bf16 v[38:41], v[100:103], v[72:75], v[46:49]
	v_mfma_f32_16x16x32_bf16 v[46:49], v[104:107], v[72:75], v[58:61]
	v_mfma_f32_16x16x32_bf16 v[50:53], v[108:111], v[72:75], v[50:53]
	v_mfma_f32_16x16x32_bf16 v[42:45], v[96:99], v[76:79], v[42:45]
	v_mfma_f32_16x16x32_bf16 v[58:61], v[100:103], v[76:79], v[62:65]
	v_mfma_f32_16x16x32_bf16 v[62:65], v[104:107], v[76:79], v[68:71]
	v_mfma_f32_16x16x32_bf16 v[54:57], v[108:111], v[76:79], v[54:57]
	v_mfma_f32_16x16x32_bf16 v[34:37], v[96:99], v[92:95], v[34:37]
	v_mfma_f32_16x16x32_bf16 v[30:33], v[100:103], v[92:95], v[30:33]
	v_mfma_f32_16x16x32_bf16 v[26:29], v[104:107], v[92:95], v[26:29]
	v_mfma_f32_16x16x32_bf16 v[18:21], v[108:111], v[92:95], v[18:21]
	ds_read_b128 v[68:71], v16
	ds_read_b128 v[72:75], v16 offset:2048
	ds_read_b128 v[76:79], v16 offset:4096
	ds_read_b128 v[92:95], v16 offset:6144
	ds_read_b128 v[96:99], v17
	ds_read_b128 v[100:103], v17 offset:2048
	ds_read_b128 v[104:107], v17 offset:4096
	ds_read_b128 v[108:111], v17 offset:6144
	s_waitcnt lgkmcnt(8)
	v_mfma_f32_16x16x32_bf16 v[80:83], v[128:131], v[112:115], v[80:83]
	v_mfma_f32_16x16x32_bf16 v[84:87], v[132:135], v[112:115], v[84:87]
	v_mfma_f32_16x16x32_bf16 v[88:91], v[136:139], v[112:115], v[88:91]
	v_mfma_f32_16x16x32_bf16 v[2:5], v[12:15], v[112:115], v[2:5]
	v_mfma_f32_16x16x32_bf16 v[22:25], v[128:131], v[116:119], v[22:25]
	v_mfma_f32_16x16x32_bf16 v[38:41], v[132:135], v[116:119], v[38:41]
	v_mfma_f32_16x16x32_bf16 v[46:49], v[136:139], v[116:119], v[46:49]
	v_mfma_f32_16x16x32_bf16 v[50:53], v[12:15], v[116:119], v[50:53]
	v_mfma_f32_16x16x32_bf16 v[42:45], v[128:131], v[120:123], v[42:45]
	v_mfma_f32_16x16x32_bf16 v[58:61], v[132:135], v[120:123], v[58:61]
	v_mfma_f32_16x16x32_bf16 v[62:65], v[136:139], v[120:123], v[62:65]
	v_mfma_f32_16x16x32_bf16 v[54:57], v[12:15], v[120:123], v[54:57]
	v_mfma_f32_16x16x32_bf16 v[34:37], v[128:131], v[124:127], v[34:37]
	v_mfma_f32_16x16x32_bf16 v[30:33], v[132:135], v[124:127], v[30:33]
	v_mfma_f32_16x16x32_bf16 v[26:29], v[136:139], v[124:127], v[26:29]
	v_mfma_f32_16x16x32_bf16 v[12:15], v[12:15], v[124:127], v[18:21]
	s_waitcnt vmcnt(0) lgkmcnt(0)
	s_barrier
	s_nop 1
	ds_read_b128 v[16:19], v8
	ds_read_b128 v[112:115], v8 offset:2048
	ds_read_b128 v[116:119], v8 offset:4096
	ds_read_b128 v[120:123], v8 offset:6144
	ds_read_b128 v[124:127], v9 offset:16384
	ds_read_b128 v[128:131], v9 offset:18432
	ds_read_b128 v[132:135], v9 offset:20480
	ds_read_b128 v[6:9], v9 offset:22528
	v_mfma_f32_16x16x32_bf16 v[80:83], v[96:99], v[68:71], v[80:83]
	v_mfma_f32_16x16x32_bf16 v[84:87], v[100:103], v[68:71], v[84:87]
	v_mfma_f32_16x16x32_bf16 v[88:91], v[104:107], v[68:71], v[88:91]
	v_mfma_f32_16x16x32_bf16 v[2:5], v[108:111], v[68:71], v[2:5]
	v_mfma_f32_16x16x32_bf16 v[20:23], v[96:99], v[72:75], v[22:25]
	v_mfma_f32_16x16x32_bf16 v[38:41], v[100:103], v[72:75], v[38:41]
	v_mfma_f32_16x16x32_bf16 v[46:49], v[104:107], v[72:75], v[46:49]
	v_mfma_f32_16x16x32_bf16 v[50:53], v[108:111], v[72:75], v[50:53]
	v_mfma_f32_16x16x32_bf16 v[42:45], v[96:99], v[76:79], v[42:45]
	v_mfma_f32_16x16x32_bf16 v[58:61], v[100:103], v[76:79], v[58:61]
	v_mfma_f32_16x16x32_bf16 v[62:65], v[104:107], v[76:79], v[62:65]
	v_mfma_f32_16x16x32_bf16 v[54:57], v[108:111], v[76:79], v[54:57]
	v_mfma_f32_16x16x32_bf16 v[34:37], v[96:99], v[92:95], v[34:37]
	v_mfma_f32_16x16x32_bf16 v[30:33], v[100:103], v[92:95], v[30:33]
	v_mfma_f32_16x16x32_bf16 v[24:27], v[104:107], v[92:95], v[26:29]
	v_mfma_f32_16x16x32_bf16 v[12:15], v[108:111], v[92:95], v[12:15]
	ds_read_b128 v[68:71], v10
	ds_read_b128 v[72:75], v10 offset:2048
	ds_read_b128 v[76:79], v10 offset:4096
	ds_read_b128 v[92:95], v10 offset:6144
	ds_read_b128 v[96:99], v11 offset:16384
	ds_read_b128 v[100:103], v11 offset:18432
	ds_read_b128 v[104:107], v11 offset:20480
	ds_read_b128 v[108:111], v11 offset:22528
	s_waitcnt lgkmcnt(8)
	v_mfma_f32_16x16x32_bf16 v[80:83], v[124:127], v[16:19], v[80:83]
	v_mfma_f32_16x16x32_bf16 v[84:87], v[128:131], v[16:19], v[84:87]
	v_mfma_f32_16x16x32_bf16 v[88:91], v[132:135], v[16:19], v[88:91]
	v_mfma_f32_16x16x32_bf16 v[2:5], v[6:9], v[16:19], v[2:5]
	v_mfma_f32_16x16x32_bf16 v[16:19], v[124:127], v[112:115], v[20:23]
	v_mfma_f32_16x16x32_bf16 v[20:23], v[128:131], v[112:115], v[38:41]
	v_mfma_f32_16x16x32_bf16 v[38:41], v[132:135], v[112:115], v[46:49]
	v_mfma_f32_16x16x32_bf16 v[112:115], v[6:9], v[112:115], v[50:53]
	v_mfma_f32_16x16x32_bf16 v[136:139], v[124:127], v[116:119], v[42:45]
	v_mfma_f32_16x16x32_bf16 v[140:143], v[128:131], v[116:119], v[58:61]
	v_mfma_f32_16x16x32_bf16 v[144:147], v[132:135], v[116:119], v[62:65]
	v_mfma_f32_16x16x32_bf16 v[116:119], v[6:9], v[116:119], v[54:57]
	v_mfma_f32_16x16x32_bf16 v[124:127], v[124:127], v[120:123], v[34:37]
	v_mfma_f32_16x16x32_bf16 v[128:131], v[128:131], v[120:123], v[30:33]
	v_mfma_f32_16x16x32_bf16 v[132:135], v[132:135], v[120:123], v[24:27]
	v_mfma_f32_16x16x32_bf16 v[120:123], v[6:9], v[120:123], v[12:15]
	s_waitcnt vmcnt(0) lgkmcnt(0)
	s_barrier
	v_mfma_f32_16x16x32_bf16 v[58:61], v[96:99], v[68:71], v[80:83]
	v_mfma_f32_16x16x32_bf16 v[62:65], v[100:103], v[68:71], v[84:87]
	v_mfma_f32_16x16x32_bf16 v[54:57], v[104:107], v[68:71], v[88:91]
	v_mfma_f32_16x16x32_bf16 v[50:53], v[108:111], v[68:71], v[2:5]
	v_mfma_f32_16x16x32_bf16 v[42:45], v[96:99], v[72:75], v[16:19]
	v_mfma_f32_16x16x32_bf16 v[46:49], v[100:103], v[72:75], v[20:23]
	v_mfma_f32_16x16x32_bf16 v[38:41], v[104:107], v[72:75], v[38:41]
	v_mfma_f32_16x16x32_bf16 v[34:37], v[108:111], v[72:75], v[112:115]
	v_mfma_f32_16x16x32_bf16 v[26:29], v[96:99], v[76:79], v[136:139]
	v_mfma_f32_16x16x32_bf16 v[30:33], v[100:103], v[76:79], v[140:143]
	v_mfma_f32_16x16x32_bf16 v[22:25], v[104:107], v[76:79], v[144:147]
	v_mfma_f32_16x16x32_bf16 v[18:21], v[108:111], v[76:79], v[116:119]
	v_mfma_f32_16x16x32_bf16 v[10:13], v[96:99], v[92:95], v[124:127]
	v_mfma_f32_16x16x32_bf16 v[14:17], v[100:103], v[92:95], v[128:131]
	v_mfma_f32_16x16x32_bf16 v[6:9], v[104:107], v[92:95], v[132:135]
	v_mfma_f32_16x16x32_bf16 v[2:5], v[108:111], v[92:95], v[120:123]
	v_ashrrev_i32_e32 v66, 2, v1
	v_and_b32_e32 v66, 0xffffffc0, v66
	v_add_u32_e32 v66, s4, v66
	s_ashr_i32 s47, s46, 31
	v_and_or_b32 v68, v1, 15, v66
	s_lshl_b64 s[4:5], s[46:47], 20
	v_ashrrev_i32_e32 v69, 31, v68
	s_add_u32 s4, s22, s4
	s_addc_u32 s5, s23, s5
	v_lshlrev_b64 v[70:71], 11, v[68:69]
	v_lshl_add_u64 v[70:71], s[4:5], 0, v[70:71]
	s_lshl_b32 s2, s59, 8
	v_lshrrev_b32_e32 v74, 1, v1
	v_lshl_add_u64 v[70:71], v[70:71], 0, s[2:3]
	v_and_b32_e32 v66, 0xc0, v1
	v_mul_f32_e32 v1, 0xbfb8aa3b, v58
	v_lshl_add_u64 v[72:73], v[70:71], 0, v[66:67]
	v_and_b32_e32 v70, 24, v74
	v_exp_f32_e32 v74, v1
	v_mul_f32_e32 v1, 0xbfb8aa3b, v59
	v_exp_f32_e32 v75, v1
	v_mov_b32_e32 v71, v67
	v_lshl_add_u64 v[72:73], v[72:73], 0, v[70:71]
	s_waitcnt lgkmcnt(0)
	v_pk_add_f32 v[74:75], v[74:75], 1.0 op_sel_hi:[1,0]
	s_barrier
	s_lshr_b32 s58, s39, 7
	s_add_i32 s58, s98, s58
	s_cmpk_ge_i32 s58, 0x800
	s_cbranch_scc1 .Lpf7_p2_skip
	s_mov_b32 s59, s58
	s_cmp_lg_u32 s39, 0x8000
	s_cbranch_scc1 .Lpf7_p2_nomap
	s_lshr_b32 s60, s58, 8
	s_bfe_u32 s61, s58, 0x30005
	s_and_b32 s62, s58, 31
	s_lshr_b32 s63, s60, 2
	s_lshl_b32 s63, s63, 3
	s_add_i32 s61, s61, s63
	s_and_b32 s60, s60, 3
	s_lshr_b32 s63, s60, 1
	s_xor_b32 s60, s60, s63
	s_and_b32 s60, s60, 1
	s_lshl_b32 s63, s63, 3
	s_lshr_b32 s64, s62, 2
	s_add_i32 s63, s63, s64
	s_and_b32 s62, s62, 3
	s_lshl_b32 s60, s60, 2
	s_add_i32 s60, s60, s62
	s_lshl_b32 s61, s61, 7
	s_lshl_b32 s60, s60, 4
	s_add_i32 s61, s61, s60
	s_add_i32 s59, s61, s63
.Lpf7_p2_nomap:
	s_ashr_i32 s60, s59, 7
	s_ashr_i32 s61, s60, 31
	s_lshl_b64 s[60:61], s[60:61], 22
	s_add_u32 s60, s82, s60
	s_addc_u32 s61, s83, s61
	s_bfe_u32 s62, s59, 0x30004
	s_lshl_b32 s62, s62, 19
	s_add_u32 s60, s60, s62
	s_addc_u32 s61, s61, 0
	s_bfe_u32 s62, s59, 0x20002
	s_lshl_b32 s62, s62, 12
	s_mov_b32 s63, 0
	v_ashrrev_i32_e32 v202, 3, v0
	v_lshrrev_b32_e32 v206, 4, v0
	v_xor_b32_e32 v206, v206, v0
	v_lshlrev_b32_e32 v206, 4, v206
	v_and_b32_e32 v206, 0x70, v206
	v_mov_b32_e32 v207, 0
	v_ashrrev_i32_e32 v203, 31, v202
	v_lshlrev_b64 v[202:203], 11, v[202:203]
	v_lshl_add_u64 v[202:203], s[60:61], 0, v[202:203]
	v_lshl_add_u64 v[202:203], v[202:203], 0, v[206:207]
	v_mov_b32_e32 v208, v200
	v_ashrrev_i32_e32 v209, 31, v200
	v_mov_b32_e32 v210, v201
	v_ashrrev_i32_e32 v211, 31, v201
	v_lshl_add_u64 v[208:209], v[208:209], 0, s[62:63]
	v_lshl_add_u64 v[210:211], v[210:211], 0, s[62:63]
	v_lshlrev_b64 v[208:209], 11, v[208:209]
	v_lshlrev_b64 v[210:211], 11, v[210:211]
	v_lshl_add_u64 v[208:209], s[8:9], 0, v[208:209]
	v_lshl_add_u64 v[210:211], s[8:9], 0, v[210:211]
	v_lshl_add_u64 v[208:209], v[208:209], 0, v[206:207]
	v_lshl_add_u64 v[210:211], v[210:211], 0, v[206:207]
	v_readfirstlane_b32 s64, v0
	s_nop 3
	s_lshl_b32 s64, s64, 4
	s_and_b32 s64, s64, 0xfffffc00
	s_mov_b32 m0, s64
	s_nop 0
	global_load_lds_dwordx4 v[208:209], off
	s_add_i32 m0, s64, 0x2000
	s_nop 0
	global_load_lds_dwordx4 v[210:211], off
	s_add_i32 m0, s64, 0x4000
	s_nop 0
	global_load_lds_dwordx4 v[202:203], off
	s_mov_b64 s[60:61], 0x20000
	v_lshl_add_u64 v[212:213], v[202:203], 0, s[60:61]
	s_add_i32 m0, s64, 0x6000
	s_nop 0
	global_load_lds_dwordx4 v[212:213], off
	s_mov_b64 s[60:61], 0x40000
	v_lshl_add_u64 v[214:215], v[202:203], 0, s[60:61]
	s_add_i32 m0, s64, 0x8000
	s_nop 0
	global_load_lds_dwordx4 v[214:215], off
	s_mov_b64 s[60:61], 0x60000
	v_lshl_add_u64 v[216:217], v[202:203], 0, s[60:61]
	s_add_i32 m0, s64, 0xa000
	s_nop 0
	global_load_lds_dwordx4 v[216:217], off
	s_mov_b64 s[60:61], 0x80
	v_lshl_add_u64 v[218:219], v[208:209], 0, s[60:61]
	s_add_i32 m0, s64, 0xc000
	s_nop 0
	global_load_lds_dwordx4 v[218:219], off
	s_mov_b64 s[60:61], 0x80
	v_lshl_add_u64 v[220:221], v[210:211], 0, s[60:61]
	s_add_i32 m0, s64, 0xe000
	s_nop 0
	global_load_lds_dwordx4 v[220:221], off
	s_mov_b64 s[60:61], 0x80
	v_lshl_add_u64 v[222:223], v[202:203], 0, s[60:61]
	s_add_i32 m0, s64, 0x10000
	s_nop 0
	global_load_lds_dwordx4 v[222:223], off
	s_mov_b64 s[60:61], 0x20080
	v_lshl_add_u64 v[224:225], v[202:203], 0, s[60:61]
	s_add_i32 m0, s64, 0x12000
	s_nop 0
	global_load_lds_dwordx4 v[224:225], off
	s_mov_b64 s[60:61], 0x40080
	v_lshl_add_u64 v[226:227], v[202:203], 0, s[60:61]
	s_add_i32 m0, s64, 0x14000
	s_nop 0
	global_load_lds_dwordx4 v[226:227], off
	s_mov_b64 s[60:61], 0x60080
	v_lshl_add_u64 v[228:229], v[202:203], 0, s[60:61]
	s_add_i32 m0, s64, 0x16000
	s_nop 0
	global_load_lds_dwordx4 v[228:229], off
	s_mov_b32 s99, 1
.Lpf7_p2_skip:
	v_div_scale_f32 v1, s[46:47], v75, v75, v59
	v_rcp_f32_e32 v69, v1
	s_add_i32 s98, s98, s66
	s_add_i32 s38, s38, s39
	v_fma_f32 v76, -v1, v69, 1.0
	v_fmac_f32_e32 v69, v76, v69
	v_div_scale_f32 v76, vcc, v59, v75, v59
	v_mul_f32_e32 v77, v76, v69
	v_fma_f32 v78, -v1, v77, v76
	v_fmac_f32_e32 v77, v78, v69
	v_fma_f32 v1, -v1, v77, v76
	v_div_fmas_f32 v1, v1, v69, v77
	v_div_fixup_f32 v59, v1, v75, v59
	v_div_scale_f32 v1, s[46:47], v74, v74, v58
	v_rcp_f32_e32 v69, v1
	s_cmpk_lt_i32 s98, 0x800
	v_fma_f32 v75, -v1, v69, 1.0
	v_fmac_f32_e32 v69, v75, v69
	v_div_scale_f32 v75, vcc, v58, v74, v58
	v_mul_f32_e32 v76, v75, v69
	v_fma_f32 v77, -v1, v76, v75
	v_fmac_f32_e32 v76, v77, v69
	v_fma_f32 v1, -v1, v76, v75
	v_div_fmas_f32 v1, v1, v69, v76
	v_div_fixup_f32 v58, v1, v74, v58
	v_mul_f32_e32 v1, 0xbfb8aa3b, v60
	v_pk_mul_f32 v[58:59], v[62:63], v[58:59]
	v_exp_f32_e32 v62, v1
	v_mul_f32_e32 v1, 0xbfb8aa3b, v61
	v_exp_f32_e32 v63, v1
	v_cvt_pk_bf16_f32 v58, v58, v59
	v_pk_add_f32 v[62:63], v[62:63], 1.0 op_sel_hi:[1,0]
	s_nop 0
	v_div_scale_f32 v1, s[46:47], v63, v63, v61
	v_rcp_f32_e32 v69, v1
	s_nop 0
	v_fma_f32 v74, -v1, v69, 1.0
	v_fmac_f32_e32 v69, v74, v69
	v_div_scale_f32 v74, vcc, v61, v63, v61
	v_mul_f32_e32 v75, v74, v69
	v_fma_f32 v76, -v1, v75, v74
	v_fmac_f32_e32 v75, v76, v69
	v_fma_f32 v1, -v1, v75, v74
	v_div_fmas_f32 v1, v1, v69, v75
	v_div_fixup_f32 v61, v1, v63, v61
	v_div_scale_f32 v1, s[46:47], v62, v62, v60
	v_rcp_f32_e32 v63, v1
	s_nop 0
	v_fma_f32 v69, -v1, v63, 1.0
	v_fmac_f32_e32 v63, v69, v63
	v_div_scale_f32 v69, vcc, v60, v62, v60
	v_mul_f32_e32 v74, v69, v63
	v_fma_f32 v75, -v1, v74, v69
	v_fmac_f32_e32 v74, v75, v63
	v_fma_f32 v1, -v1, v74, v69
	v_div_fmas_f32 v1, v1, v63, v74
	v_div_fixup_f32 v60, v1, v62, v60
	v_pk_mul_f32 v[60:61], v[64:65], v[60:61]
	v_mul_f32_e32 v1, 0xbfb8aa3b, v54
	v_cvt_pk_bf16_f32 v59, v60, v61
	global_store_dwordx2 v[72:73], v[58:59], off
	v_exp_f32_e32 v58, v1
	v_mul_f32_e32 v1, 0xbfb8aa3b, v55
	v_exp_f32_e32 v59, v1
	s_nop 0
	v_pk_add_f32 v[58:59], v[58:59], 1.0 op_sel_hi:[1,0]
	s_nop 0
	v_div_scale_f32 v1, s[46:47], v59, v59, v55
	v_rcp_f32_e32 v60, v1
	s_nop 0
	v_fma_f32 v61, -v1, v60, 1.0
	v_fmac_f32_e32 v60, v61, v60
	v_div_scale_f32 v61, vcc, v55, v59, v55
	v_mul_f32_e32 v62, v61, v60
	v_fma_f32 v63, -v1, v62, v61
	v_fmac_f32_e32 v62, v63, v60
	v_fma_f32 v1, -v1, v62, v61
	v_div_fmas_f32 v1, v1, v60, v62
	v_div_fixup_f32 v55, v1, v59, v55
	v_div_scale_f32 v1, s[46:47], v58, v58, v54
	v_rcp_f32_e32 v59, v1
	s_nop 0
	v_fma_f32 v60, -v1, v59, 1.0
	v_fmac_f32_e32 v59, v60, v59
	v_div_scale_f32 v60, vcc, v54, v58, v54
	v_mul_f32_e32 v61, v60, v59
	v_fma_f32 v62, -v1, v61, v60
	v_fmac_f32_e32 v61, v62, v59
	v_fma_f32 v1, -v1, v61, v60
	v_div_fmas_f32 v1, v1, v59, v61
	v_div_fixup_f32 v54, v1, v58, v54
	v_mul_f32_e32 v1, 0xbfb8aa3b, v56
	v_pk_mul_f32 v[50:51], v[50:51], v[54:55]
	v_exp_f32_e32 v54, v1
	v_mul_f32_e32 v1, 0xbfb8aa3b, v57
	v_exp_f32_e32 v55, v1
	v_cvt_pk_bf16_f32 v50, v50, v51
	v_pk_add_f32 v[54:55], v[54:55], 1.0 op_sel_hi:[1,0]
	s_nop 0
	v_div_scale_f32 v1, s[46:47], v55, v55, v57
	v_rcp_f32_e32 v58, v1
	s_nop 0
	v_fma_f32 v59, -v1, v58, 1.0
	v_fmac_f32_e32 v58, v59, v58
	v_div_scale_f32 v59, vcc, v57, v55, v57
	v_mul_f32_e32 v60, v59, v58
	v_fma_f32 v61, -v1, v60, v59
	v_fmac_f32_e32 v60, v61, v58
	v_fma_f32 v1, -v1, v60, v59
	v_div_fmas_f32 v1, v1, v58, v60
	v_div_fixup_f32 v55, v1, v55, v57
	v_div_scale_f32 v1, s[46:47], v54, v54, v56
	v_rcp_f32_e32 v57, v1
	s_nop 0
	v_fma_f32 v58, -v1, v57, 1.0
	v_fmac_f32_e32 v57, v58, v57
	v_div_scale_f32 v58, vcc, v56, v54, v56
	v_mul_f32_e32 v59, v58, v57
	v_fma_f32 v60, -v1, v59, v58
	v_fmac_f32_e32 v59, v60, v57
	v_fma_f32 v1, -v1, v59, v58
	v_div_fmas_f32 v1, v1, v57, v59
	v_div_fixup_f32 v54, v1, v54, v56
	v_pk_mul_f32 v[52:53], v[52:53], v[54:55]
	v_mul_f32_e32 v1, 0xbfb8aa3b, v42
	v_cvt_pk_bf16_f32 v51, v52, v53
	v_exp_f32_e32 v52, v1
	v_mul_f32_e32 v1, 0xbfb8aa3b, v43
	v_exp_f32_e32 v53, v1
	global_store_dwordx2 v[72:73], v[50:51], off offset:32
	v_or_b32_e32 v50, 16, v68
	v_ashrrev_i32_e32 v51, 31, v50
	v_pk_add_f32 v[52:53], v[52:53], 1.0 op_sel_hi:[1,0]
	v_lshlrev_b64 v[50:51], 11, v[50:51]
	v_div_scale_f32 v1, s[46:47], v53, v53, v43
	v_rcp_f32_e32 v54, v1
	v_lshl_add_u64 v[50:51], s[4:5], 0, v[50:51]
	v_lshl_add_u64 v[50:51], v[50:51], 0, s[2:3]
	v_lshl_add_u64 v[50:51], v[50:51], 0, v[66:67]
	v_fma_f32 v55, -v1, v54, 1.0
	v_fmac_f32_e32 v54, v55, v54
	v_div_scale_f32 v55, vcc, v43, v53, v43
	v_mul_f32_e32 v56, v55, v54
	v_fma_f32 v57, -v1, v56, v55
	v_fmac_f32_e32 v56, v57, v54
	v_fma_f32 v1, -v1, v56, v55
	v_div_fmas_f32 v1, v1, v54, v56
	v_div_fixup_f32 v43, v1, v53, v43
	v_div_scale_f32 v1, s[46:47], v52, v52, v42
	v_rcp_f32_e32 v53, v1
	v_lshl_add_u64 v[50:51], v[50:51], 0, v[70:71]
	v_fma_f32 v54, -v1, v53, 1.0
	v_fmac_f32_e32 v53, v54, v53
	v_div_scale_f32 v54, vcc, v42, v52, v42
	v_mul_f32_e32 v55, v54, v53
	v_fma_f32 v56, -v1, v55, v54
	v_fmac_f32_e32 v55, v56, v53
	v_fma_f32 v1, -v1, v55, v54
	v_div_fmas_f32 v1, v1, v53, v55
	v_div_fixup_f32 v42, v1, v52, v42
	v_mul_f32_e32 v1, 0xbfb8aa3b, v44
	v_pk_mul_f32 v[42:43], v[46:47], v[42:43]
	v_exp_f32_e32 v46, v1
	v_mul_f32_e32 v1, 0xbfb8aa3b, v45
	v_exp_f32_e32 v47, v1
	v_cvt_pk_bf16_f32 v42, v42, v43
	v_pk_add_f32 v[46:47], v[46:47], 1.0 op_sel_hi:[1,0]
	s_nop 0
	v_div_scale_f32 v1, s[46:47], v47, v47, v45
	v_rcp_f32_e32 v52, v1
	s_nop 0
	v_fma_f32 v53, -v1, v52, 1.0
	v_fmac_f32_e32 v52, v53, v52
	v_div_scale_f32 v53, vcc, v45, v47, v45
	v_mul_f32_e32 v54, v53, v52
	v_fma_f32 v55, -v1, v54, v53
	v_fmac_f32_e32 v54, v55, v52
	v_fma_f32 v1, -v1, v54, v53
	v_div_fmas_f32 v1, v1, v52, v54
	v_div_fixup_f32 v45, v1, v47, v45
	v_div_scale_f32 v1, s[46:47], v46, v46, v44
	v_rcp_f32_e32 v47, v1
	s_nop 0
	v_fma_f32 v52, -v1, v47, 1.0
	v_fmac_f32_e32 v47, v52, v47
	v_div_scale_f32 v52, vcc, v44, v46, v44
	v_mul_f32_e32 v53, v52, v47
	v_fma_f32 v54, -v1, v53, v52
	v_fmac_f32_e32 v53, v54, v47
	v_fma_f32 v1, -v1, v53, v52
	v_div_fmas_f32 v1, v1, v47, v53
	v_div_fixup_f32 v44, v1, v46, v44
	v_pk_mul_f32 v[44:45], v[48:49], v[44:45]
	v_mul_f32_e32 v1, 0xbfb8aa3b, v38
	v_cvt_pk_bf16_f32 v43, v44, v45
	global_store_dwordx2 v[50:51], v[42:43], off
	v_exp_f32_e32 v42, v1
	v_mul_f32_e32 v1, 0xbfb8aa3b, v39
	v_exp_f32_e32 v43, v1
	s_nop 0
	v_pk_add_f32 v[42:43], v[42:43], 1.0 op_sel_hi:[1,0]
	s_nop 0
	v_div_scale_f32 v1, s[46:47], v43, v43, v39
	v_rcp_f32_e32 v44, v1
	s_nop 0
	v_fma_f32 v45, -v1, v44, 1.0
	v_fmac_f32_e32 v44, v45, v44
	v_div_scale_f32 v45, vcc, v39, v43, v39
	v_mul_f32_e32 v46, v45, v44
	v_fma_f32 v47, -v1, v46, v45
	v_fmac_f32_e32 v46, v47, v44
	v_fma_f32 v1, -v1, v46, v45
	v_div_fmas_f32 v1, v1, v44, v46
	v_div_fixup_f32 v39, v1, v43, v39
	v_div_scale_f32 v1, s[46:47], v42, v42, v38
	v_rcp_f32_e32 v43, v1
	s_nop 0
	v_fma_f32 v44, -v1, v43, 1.0
	v_fmac_f32_e32 v43, v44, v43
	v_div_scale_f32 v44, vcc, v38, v42, v38
	v_mul_f32_e32 v45, v44, v43
	v_fma_f32 v46, -v1, v45, v44
	v_fmac_f32_e32 v45, v46, v43
	v_fma_f32 v1, -v1, v45, v44
	v_div_fmas_f32 v1, v1, v43, v45
	v_div_fixup_f32 v38, v1, v42, v38
	v_mul_f32_e32 v1, 0xbfb8aa3b, v40
	v_pk_mul_f32 v[34:35], v[34:35], v[38:39]
	v_exp_f32_e32 v38, v1
	v_mul_f32_e32 v1, 0xbfb8aa3b, v41
	v_exp_f32_e32 v39, v1
	v_cvt_pk_bf16_f32 v34, v34, v35
	v_pk_add_f32 v[38:39], v[38:39], 1.0 op_sel_hi:[1,0]
	s_nop 0
	v_div_scale_f32 v1, s[46:47], v39, v39, v41
	v_rcp_f32_e32 v42, v1
	s_nop 0
	v_fma_f32 v43, -v1, v42, 1.0
	v_fmac_f32_e32 v42, v43, v42
	v_div_scale_f32 v43, vcc, v41, v39, v41
	v_mul_f32_e32 v44, v43, v42
	v_fma_f32 v45, -v1, v44, v43
	v_fmac_f32_e32 v44, v45, v42
	v_fma_f32 v1, -v1, v44, v43
	v_div_fmas_f32 v1, v1, v42, v44
	v_div_fixup_f32 v39, v1, v39, v41
	v_div_scale_f32 v1, s[46:47], v38, v38, v40
	v_rcp_f32_e32 v41, v1
	s_nop 0
	v_fma_f32 v42, -v1, v41, 1.0
	v_fmac_f32_e32 v41, v42, v41
	v_div_scale_f32 v42, vcc, v40, v38, v40
	v_mul_f32_e32 v43, v42, v41
	v_fma_f32 v44, -v1, v43, v42
	v_fmac_f32_e32 v43, v44, v41
	v_fma_f32 v1, -v1, v43, v42
	v_div_fmas_f32 v1, v1, v41, v43
	v_div_fixup_f32 v38, v1, v38, v40
	v_pk_mul_f32 v[36:37], v[36:37], v[38:39]
	v_mul_f32_e32 v1, 0xbfb8aa3b, v26
	v_cvt_pk_bf16_f32 v35, v36, v37
	v_exp_f32_e32 v36, v1
	v_mul_f32_e32 v1, 0xbfb8aa3b, v27
	v_exp_f32_e32 v37, v1
	global_store_dwordx2 v[50:51], v[34:35], off offset:32
	v_or_b32_e32 v34, 32, v68
	v_ashrrev_i32_e32 v35, 31, v34
	v_pk_add_f32 v[36:37], v[36:37], 1.0 op_sel_hi:[1,0]
	v_lshlrev_b64 v[34:35], 11, v[34:35]
	v_div_scale_f32 v1, s[46:47], v37, v37, v27
	v_rcp_f32_e32 v38, v1
	v_lshl_add_u64 v[34:35], s[4:5], 0, v[34:35]
	v_lshl_add_u64 v[34:35], v[34:35], 0, s[2:3]
	v_lshl_add_u64 v[34:35], v[34:35], 0, v[66:67]
	v_fma_f32 v39, -v1, v38, 1.0
	v_fmac_f32_e32 v38, v39, v38
	v_div_scale_f32 v39, vcc, v27, v37, v27
	v_mul_f32_e32 v40, v39, v38
	v_fma_f32 v41, -v1, v40, v39
	v_fmac_f32_e32 v40, v41, v38
	v_fma_f32 v1, -v1, v40, v39
	v_div_fmas_f32 v1, v1, v38, v40
	v_div_fixup_f32 v27, v1, v37, v27
	v_div_scale_f32 v1, s[46:47], v36, v36, v26
	v_rcp_f32_e32 v37, v1
	v_lshl_add_u64 v[34:35], v[34:35], 0, v[70:71]
	v_fma_f32 v38, -v1, v37, 1.0
	v_fmac_f32_e32 v37, v38, v37
	v_div_scale_f32 v38, vcc, v26, v36, v26
	v_mul_f32_e32 v39, v38, v37
	v_fma_f32 v40, -v1, v39, v38
	v_fmac_f32_e32 v39, v40, v37
	v_fma_f32 v1, -v1, v39, v38
	v_div_fmas_f32 v1, v1, v37, v39
	v_div_fixup_f32 v26, v1, v36, v26
	v_mul_f32_e32 v1, 0xbfb8aa3b, v28
	v_pk_mul_f32 v[26:27], v[30:31], v[26:27]
	v_exp_f32_e32 v30, v1
	v_mul_f32_e32 v1, 0xbfb8aa3b, v29
	v_exp_f32_e32 v31, v1
	v_cvt_pk_bf16_f32 v26, v26, v27
	v_pk_add_f32 v[30:31], v[30:31], 1.0 op_sel_hi:[1,0]
	s_nop 0
	v_div_scale_f32 v1, s[46:47], v31, v31, v29
	v_rcp_f32_e32 v36, v1
	s_nop 0
	v_fma_f32 v37, -v1, v36, 1.0
	v_fmac_f32_e32 v36, v37, v36
	v_div_scale_f32 v37, vcc, v29, v31, v29
	v_mul_f32_e32 v38, v37, v36
	v_fma_f32 v39, -v1, v38, v37
	v_fmac_f32_e32 v38, v39, v36
	v_fma_f32 v1, -v1, v38, v37
	v_div_fmas_f32 v1, v1, v36, v38
	v_div_fixup_f32 v29, v1, v31, v29
	v_div_scale_f32 v1, s[46:47], v30, v30, v28
	v_rcp_f32_e32 v31, v1
	s_nop 0
	v_fma_f32 v36, -v1, v31, 1.0
	v_fmac_f32_e32 v31, v36, v31
	v_div_scale_f32 v36, vcc, v28, v30, v28
	v_mul_f32_e32 v37, v36, v31
	v_fma_f32 v38, -v1, v37, v36
	v_fmac_f32_e32 v37, v38, v31
	v_fma_f32 v1, -v1, v37, v36
	v_div_fmas_f32 v1, v1, v31, v37
	v_div_fixup_f32 v28, v1, v30, v28
	v_pk_mul_f32 v[28:29], v[32:33], v[28:29]
	v_mul_f32_e32 v1, 0xbfb8aa3b, v22
	v_cvt_pk_bf16_f32 v27, v28, v29
	global_store_dwordx2 v[34:35], v[26:27], off
	v_exp_f32_e32 v26, v1
	v_mul_f32_e32 v1, 0xbfb8aa3b, v23
	v_exp_f32_e32 v27, v1
	s_nop 0
	v_pk_add_f32 v[26:27], v[26:27], 1.0 op_sel_hi:[1,0]
	s_nop 0
	v_div_scale_f32 v1, s[46:47], v27, v27, v23
	v_rcp_f32_e32 v28, v1
	s_nop 0
	v_fma_f32 v29, -v1, v28, 1.0
	v_fmac_f32_e32 v28, v29, v28
	v_div_scale_f32 v29, vcc, v23, v27, v23
	v_mul_f32_e32 v30, v29, v28
	v_fma_f32 v31, -v1, v30, v29
	v_fmac_f32_e32 v30, v31, v28
	v_fma_f32 v1, -v1, v30, v29
	v_div_fmas_f32 v1, v1, v28, v30
	v_div_fixup_f32 v23, v1, v27, v23
	v_div_scale_f32 v1, s[46:47], v26, v26, v22
	v_rcp_f32_e32 v27, v1
	s_nop 0
	v_fma_f32 v28, -v1, v27, 1.0
	v_fmac_f32_e32 v27, v28, v27
	v_div_scale_f32 v28, vcc, v22, v26, v22
	v_mul_f32_e32 v29, v28, v27
	v_fma_f32 v30, -v1, v29, v28
	v_fmac_f32_e32 v29, v30, v27
	v_fma_f32 v1, -v1, v29, v28
	v_div_fmas_f32 v1, v1, v27, v29
	v_div_fixup_f32 v22, v1, v26, v22
	v_mul_f32_e32 v1, 0xbfb8aa3b, v24
	v_pk_mul_f32 v[18:19], v[18:19], v[22:23]
	v_exp_f32_e32 v22, v1
	v_mul_f32_e32 v1, 0xbfb8aa3b, v25
	v_exp_f32_e32 v23, v1
	v_cvt_pk_bf16_f32 v18, v18, v19
	v_pk_add_f32 v[22:23], v[22:23], 1.0 op_sel_hi:[1,0]
	s_nop 0
	v_div_scale_f32 v1, s[46:47], v23, v23, v25
	v_rcp_f32_e32 v26, v1
	s_nop 0
	v_fma_f32 v27, -v1, v26, 1.0
	v_fmac_f32_e32 v26, v27, v26
	v_div_scale_f32 v27, vcc, v25, v23, v25
	v_mul_f32_e32 v28, v27, v26
	v_fma_f32 v29, -v1, v28, v27
	v_fmac_f32_e32 v28, v29, v26
	v_fma_f32 v1, -v1, v28, v27
	v_div_fmas_f32 v1, v1, v26, v28
	v_div_fixup_f32 v23, v1, v23, v25
	v_div_scale_f32 v1, s[46:47], v22, v22, v24
	v_rcp_f32_e32 v25, v1
	s_nop 0
	v_fma_f32 v26, -v1, v25, 1.0
	v_fmac_f32_e32 v25, v26, v25
	v_div_scale_f32 v26, vcc, v24, v22, v24
	v_mul_f32_e32 v27, v26, v25
	v_fma_f32 v28, -v1, v27, v26
	v_fmac_f32_e32 v27, v28, v25
	v_fma_f32 v1, -v1, v27, v26
	v_div_fmas_f32 v1, v1, v25, v27
	v_div_fixup_f32 v22, v1, v22, v24
	v_pk_mul_f32 v[20:21], v[20:21], v[22:23]
	v_mul_f32_e32 v1, 0xbfb8aa3b, v10
	v_cvt_pk_bf16_f32 v19, v20, v21
	v_exp_f32_e32 v20, v1
	v_mul_f32_e32 v1, 0xbfb8aa3b, v11
	v_exp_f32_e32 v21, v1
	global_store_dwordx2 v[34:35], v[18:19], off offset:32
	v_or_b32_e32 v18, 48, v68
	v_ashrrev_i32_e32 v19, 31, v18
	v_lshlrev_b64 v[18:19], 11, v[18:19]
	v_pk_add_f32 v[20:21], v[20:21], 1.0 op_sel_hi:[1,0]
	v_lshl_add_u64 v[18:19], s[4:5], 0, v[18:19]
	v_div_scale_f32 v1, s[4:5], v21, v21, v11
	v_rcp_f32_e32 v22, v1
	v_lshl_add_u64 v[18:19], v[18:19], 0, s[2:3]
	v_lshl_add_u64 v[18:19], v[18:19], 0, v[66:67]
	v_lshl_add_u64 v[18:19], v[18:19], 0, v[70:71]
	v_fma_f32 v23, -v1, v22, 1.0
	v_fmac_f32_e32 v22, v23, v22
	v_div_scale_f32 v23, vcc, v11, v21, v11
	v_mul_f32_e32 v24, v23, v22
	v_fma_f32 v25, -v1, v24, v23
	v_fmac_f32_e32 v24, v25, v22
	v_fma_f32 v1, -v1, v24, v23
	v_div_fmas_f32 v1, v1, v22, v24
	v_div_fixup_f32 v11, v1, v21, v11
	v_div_scale_f32 v1, s[4:5], v20, v20, v10
	v_rcp_f32_e32 v21, v1
	s_nop 0
	v_fma_f32 v22, -v1, v21, 1.0
	v_fmac_f32_e32 v21, v22, v21
	v_div_scale_f32 v22, vcc, v10, v20, v10
	v_mul_f32_e32 v23, v22, v21
	v_fma_f32 v24, -v1, v23, v22
	v_fmac_f32_e32 v23, v24, v21
	v_fma_f32 v1, -v1, v23, v22
	v_div_fmas_f32 v1, v1, v21, v23
	v_div_fixup_f32 v10, v1, v20, v10
	v_mul_f32_e32 v1, 0xbfb8aa3b, v12
	v_pk_mul_f32 v[10:11], v[14:15], v[10:11]
	v_exp_f32_e32 v14, v1
	v_mul_f32_e32 v1, 0xbfb8aa3b, v13
	v_exp_f32_e32 v15, v1
	v_cvt_pk_bf16_f32 v10, v10, v11
	v_pk_add_f32 v[14:15], v[14:15], 1.0 op_sel_hi:[1,0]
	s_nop 0
	v_div_scale_f32 v1, s[4:5], v15, v15, v13
	v_rcp_f32_e32 v20, v1
	s_nop 0
	v_fma_f32 v21, -v1, v20, 1.0
	v_fmac_f32_e32 v20, v21, v20
	v_div_scale_f32 v21, vcc, v13, v15, v13
	v_mul_f32_e32 v22, v21, v20
	v_fma_f32 v23, -v1, v22, v21
	v_fmac_f32_e32 v22, v23, v20
	v_fma_f32 v1, -v1, v22, v21
	v_div_fmas_f32 v1, v1, v20, v22
	v_div_fixup_f32 v13, v1, v15, v13
	v_div_scale_f32 v1, s[4:5], v14, v14, v12
	v_rcp_f32_e32 v15, v1
	s_nop 0
	v_fma_f32 v20, -v1, v15, 1.0
	v_fmac_f32_e32 v15, v20, v15
	v_div_scale_f32 v20, vcc, v12, v14, v12
	v_mul_f32_e32 v21, v20, v15
	v_fma_f32 v22, -v1, v21, v20
	v_fmac_f32_e32 v21, v22, v15
	v_fma_f32 v1, -v1, v21, v20
	v_div_fmas_f32 v1, v1, v15, v21
	v_div_fixup_f32 v12, v1, v14, v12
	v_pk_mul_f32 v[12:13], v[16:17], v[12:13]
	v_mul_f32_e32 v1, 0xbfb8aa3b, v6
	v_cvt_pk_bf16_f32 v11, v12, v13
	global_store_dwordx2 v[18:19], v[10:11], off
	v_exp_f32_e32 v10, v1
	v_mul_f32_e32 v1, 0xbfb8aa3b, v7
	v_exp_f32_e32 v11, v1
	s_nop 0
	v_pk_add_f32 v[10:11], v[10:11], 1.0 op_sel_hi:[1,0]
	s_nop 0
	v_div_scale_f32 v1, s[4:5], v11, v11, v7
	v_rcp_f32_e32 v12, v1
	s_nop 0
	v_fma_f32 v13, -v1, v12, 1.0
	v_fmac_f32_e32 v12, v13, v12
	v_div_scale_f32 v13, vcc, v7, v11, v7
	v_mul_f32_e32 v14, v13, v12
	v_fma_f32 v15, -v1, v14, v13
	v_fmac_f32_e32 v14, v15, v12
	v_fma_f32 v1, -v1, v14, v13
	v_div_fmas_f32 v1, v1, v12, v14
	v_div_fixup_f32 v7, v1, v11, v7
	v_div_scale_f32 v1, s[4:5], v10, v10, v6
	v_rcp_f32_e32 v11, v1
	s_nop 0
	v_fma_f32 v12, -v1, v11, 1.0
	v_fmac_f32_e32 v11, v12, v11
	v_div_scale_f32 v12, vcc, v6, v10, v6
	v_mul_f32_e32 v13, v12, v11
	v_fma_f32 v14, -v1, v13, v12
	v_fmac_f32_e32 v13, v14, v11
	v_fma_f32 v1, -v1, v13, v12
	v_div_fmas_f32 v1, v1, v11, v13
	v_div_fixup_f32 v6, v1, v10, v6
	v_mul_f32_e32 v1, 0xbfb8aa3b, v8
	v_pk_mul_f32 v[2:3], v[2:3], v[6:7]
	v_exp_f32_e32 v6, v1
	v_mul_f32_e32 v1, 0xbfb8aa3b, v9
	v_exp_f32_e32 v7, v1
	v_cvt_pk_bf16_f32 v2, v2, v3
	v_pk_add_f32 v[6:7], v[6:7], 1.0 op_sel_hi:[1,0]
	s_nop 0
	v_div_scale_f32 v1, s[4:5], v7, v7, v9
	v_rcp_f32_e32 v10, v1
	s_nop 0
	v_fma_f32 v11, -v1, v10, 1.0
	v_fmac_f32_e32 v10, v11, v10
	v_div_scale_f32 v11, vcc, v9, v7, v9
	v_mul_f32_e32 v12, v11, v10
	v_fma_f32 v13, -v1, v12, v11
	v_fmac_f32_e32 v12, v13, v10
	v_fma_f32 v1, -v1, v12, v11
	v_div_fmas_f32 v1, v1, v10, v12
	v_div_fixup_f32 v7, v1, v7, v9
	v_div_scale_f32 v1, s[4:5], v6, v6, v8
	v_rcp_f32_e32 v9, v1
	s_nop 0
	v_fma_f32 v10, -v1, v9, 1.0
	v_fmac_f32_e32 v9, v10, v9
	v_div_scale_f32 v10, vcc, v8, v6, v8
	v_mul_f32_e32 v11, v10, v9
	v_fma_f32 v12, -v1, v11, v10
	v_fmac_f32_e32 v11, v12, v9
	v_fma_f32 v1, -v1, v11, v10
	v_div_fmas_f32 v1, v1, v9, v11
	v_div_fixup_f32 v6, v1, v6, v8
	v_pk_mul_f32 v[4:5], v[4:5], v[6:7]
	s_nop 0
	v_cvt_pk_bf16_f32 v3, v4, v5
	global_store_dwordx2 v[18:19], v[2:3], off offset:32
	s_cbranch_scc1 .LBB0_838
	v_readlane_b32 s0, v196, 26
	v_readlane_b32 s47, v196, 5
	v_readlane_b32 s96, v196, 24
	v_readlane_b32 s1, v196, 27
	s_mov_b32 s46, s66
	v_readlane_b32 s97, v196, 25
